# GEMM K-loops: in-loop LDS-DMA converted to saddr form (SGPR base + 32-bit VGPR offset, 15 of 16 per iteration; removes the 64-bit VALU address adds), on top of 4/4 staging rebalance
# speedup vs baseline: 1.0045x; 1.0045x over previous
; #define PG8_STAGE(bufoff, gbase, voff) do { _Pragma("unroll") for (int _i = 0; _i < 2; ++_i) \
;         __builtin_amdgcn_global_load_lds((const unsigned*)((const char*)(gbase) + (voff)[_i]), (LAS unsigned*)(lds + (bufoff) + ldsw + _i * 8192), 16, 0, 0); } while (0)
; #define PG8_LDA(dst, b, h) do { _Pragma("unroll") for (int m = 0; m < 4; ++m) _Pragma("unroll") for (int k = 0; k < 2; ++k) dst[m][k] = *(const LAS bf16x8*)(lds + PG8_SA(b, h) + aoff + m * 2048 + k * 1024); } while (0)
; #define PG8_LDB(dst, b, h) do { _Pragma("unroll") for (int n = 0; n < 2; ++n) _Pragma("unroll") for (int k = 0; k < 2; ++k) dst[n][k] = *(const LAS bf16x8*)(lds + PG8_SB(b, h) + boff + n * 2048 + k * 1024); } while (0)
; #define PG8_WAIT_V(n) asm volatile("s_waitcnt vmcnt(" #n ")" ::: "memory")
; #define PG8_WAIT_L(n) asm volatile("s_waitcnt lgkmcnt(" #n ")" ::: "memory")
; #define PG8_BAR __builtin_amdgcn_s_barrier()
; #define PG8_SCHED __builtin_amdgcn_sched_barrier(0)
; template <class Epi, class Sched, bool I8 = false>
; __device__ __forceinline__ void gemm_phase(LAS unsigned char* lds, const Gemm g, const Sched& S, const Epi& E) {
;     ...
;         for (int t = 0; t < nt; t += 2) {
;             const bool last = (t == nt - 2);
;             const char* a1 = cA + (size_t)(t + 1) * kstep;
;             const char* a2 = last ? nA : cA + (size_t)(t + 2) * kstep; const char* b2 = last ? nB : cB + (size_t)(t + 2) * kstep;
;             const char* a3 = a2 + kstep; const char* b3 = b2 + kstep;
;             PG8_LDB(B0, 0, 0); PG8_LDB(B1, 0, 1); PG8_SCHED; PG8_LDA(At, 0, 0); PG8_STAGE(PG8_SA(1, 1), a1 + hstepA, voffA);
;             PG8_WAIT_V(8); PG8_WAIT_L(0); PG8_BAR; PG8_MMA(0, 0, At, B0); PG8_MMA(0, 1, At, B1); PG8_BAR; PG8_SCHED;
;             PG8_LDA(At, 0, 1); PG8_STAGE(PG8_SB(0, 0), b2, voffB); PG8_STAGE(PG8_SB(0, 1), b2 + hstepB, voffB); PG8_STAGE(PG8_SA(0, 0), a2, voffA);
;             PG8_WAIT_V(8); PG8_WAIT_L(0); PG8_BAR; PG8_MMA(1, 0, At, B0); PG8_MMA(1, 1, At, B1); PG8_BAR; PG8_SCHED;
.LBB0_1169:
	ds_read_b128 v[90:93], v169
	ds_read_b128 v[98:101], v169 offset:1024
	ds_read_b128 v[172:175], v169 offset:2048
	ds_read_b128 v[176:179], v169 offset:3072
	ds_read_b128 v[180:183], v170
	ds_read_b128 v[184:187], v170 offset:1024
	ds_read_b128 v[188:191], v170 offset:2048
	ds_read_b128 v[192:195], v170 offset:3072
	s_add_u32 s22, s20, 0x4000
	s_addc_u32 s23, s21, 0
	s_cmp_eq_u32 s53, 28
	s_cselect_b32 s26, s49, s22
	s_cselect_b32 s27, s13, s23
	s_cselect_b32 s24, s50, s51
	s_cselect_b32 s25, s11, s52
	s_add_u32 s22, s26, 0x8000
	s_addc_u32 s23, s27, 0
	s_sub_u32 s98, s20, 0x4000
	s_subb_u32 s99, s21, 0
	s_mov_b32 m0, s43
	s_nop 0
	global_load_lds_dwordx4 v144, s[98:99]
	s_mov_b32 m0, s44
	s_nop 0
	global_load_lds_dwordx4 v140, s[98:99]
	s_add_i32 m0, s36, 0xc000
	ds_read_b128 v[196:199], v171
	ds_read_b128 v[200:203], v171 offset:1024
	ds_read_b128 v[204:207], v171 offset:2048
	ds_read_b128 v[208:211], v171 offset:3072
	ds_read_b128 v[212:215], v171 offset:4096
	ds_read_b128 v[216:219], v171 offset:5120
	ds_read_b128 v[220:223], v171 offset:6144
	ds_read_b128 v[224:227], v171 offset:7168
	global_load_lds_dwordx4 v148, s[20:21]
	s_add_i32 m0, s36, 0xe000
	s_nop 0
	global_load_lds_dwordx4 v150, s[20:21]
	s_waitcnt vmcnt(8)
	s_waitcnt lgkmcnt(0)
	s_barrier
	s_setprio 1
	s_waitcnt lgkmcnt(0)
	v_mfma_i32_16x16x64_i8 v[134:137], v[90:93], v[196:199], v[134:137]
	v_mfma_i32_16x16x64_i8 v[130:133], v[172:175], v[196:199], v[130:133]
	v_mfma_i32_16x16x64_i8 v[118:121], v[90:93], v[204:207], v[118:121]
	v_mfma_i32_16x16x64_i8 v[114:117], v[172:175], v[204:207], v[114:117]
	v_mfma_i32_16x16x64_i8 v[102:105], v[90:93], v[212:215], v[102:105]
	v_mfma_i32_16x16x64_i8 v[94:97], v[172:175], v[212:215], v[94:97]
	v_mfma_i32_16x16x64_i8 v[78:81], v[90:93], v[220:223], v[78:81]
	v_mfma_i32_16x16x64_i8 v[74:77], v[172:175], v[220:223], v[74:77]
	v_mfma_i32_16x16x64_i8 v[134:137], v[98:101], v[200:203], v[134:137]
	v_mfma_i32_16x16x64_i8 v[130:133], v[176:179], v[200:203], v[130:133]
	v_mfma_i32_16x16x64_i8 v[118:121], v[98:101], v[208:211], v[118:121]
	v_mfma_i32_16x16x64_i8 v[114:117], v[176:179], v[208:211], v[114:117]
	v_mfma_i32_16x16x64_i8 v[102:105], v[98:101], v[216:219], v[102:105]
	v_mfma_i32_16x16x64_i8 v[94:97], v[176:179], v[216:219], v[94:97]
	v_mfma_i32_16x16x64_i8 v[78:81], v[98:101], v[224:227], v[78:81]
	v_mfma_i32_16x16x64_i8 v[74:77], v[176:179], v[224:227], v[74:77]
	s_setprio 0
	s_setprio 1
	v_mfma_i32_16x16x64_i8 v[126:129], v[180:183], v[196:199], v[126:129]
	v_mfma_i32_16x16x64_i8 v[122:125], v[188:191], v[196:199], v[122:125]
	v_mfma_i32_16x16x64_i8 v[110:113], v[180:183], v[204:207], v[110:113]
	v_mfma_i32_16x16x64_i8 v[106:109], v[188:191], v[204:207], v[106:109]
	v_mfma_i32_16x16x64_i8 v[86:89], v[180:183], v[212:215], v[86:89]
	v_mfma_i32_16x16x64_i8 v[82:85], v[188:191], v[212:215], v[82:85]
	v_mfma_i32_16x16x64_i8 v[70:73], v[180:183], v[220:223], v[70:73]
	v_mfma_i32_16x16x64_i8 v[66:69], v[188:191], v[220:223], v[66:69]
	v_mfma_i32_16x16x64_i8 v[126:129], v[184:187], v[200:203], v[126:129]
	v_mfma_i32_16x16x64_i8 v[122:125], v[192:195], v[200:203], v[122:125]
	v_mfma_i32_16x16x64_i8 v[110:113], v[184:187], v[208:211], v[110:113]
	v_mfma_i32_16x16x64_i8 v[106:109], v[192:195], v[208:211], v[106:109]
	v_mfma_i32_16x16x64_i8 v[86:89], v[184:187], v[216:219], v[86:89]
	v_mfma_i32_16x16x64_i8 v[82:85], v[192:195], v[216:219], v[82:85]
	v_mfma_i32_16x16x64_i8 v[70:73], v[184:187], v[224:227], v[70:73]
	v_mfma_i32_16x16x64_i8 v[66:69], v[192:195], v[224:227], v[66:69]
	s_setprio 0
	s_barrier
	s_add_i32 s54, s46, s33
	s_mov_b32 m0, s54
	ds_read_b128 v[196:199], v171 offset:16384
	ds_read_b128 v[200:203], v171 offset:17408
	ds_read_b128 v[204:207], v171 offset:18432
	ds_read_b128 v[208:211], v171 offset:19456
	ds_read_b128 v[212:215], v171 offset:20480
	ds_read_b128 v[216:219], v171 offset:21504
	ds_read_b128 v[220:223], v171 offset:22528
	ds_read_b128 v[224:227], v171 offset:23552
	global_load_lds_dwordx4 v142, s[24:25]
	s_add_i32 m0, s54, 0x2000
	s_add_u32 s54, s24, 0x4000
	s_addc_u32 s55, s25, 0
	s_add_i32 s56, s47, s33
	global_load_lds_dwordx4 v138, s[24:25]
	s_mov_b32 m0, s56
	s_nop 0
	global_load_lds_dwordx4 v142, s[54:55]
	s_add_i32 m0, s56, 0x2000
	s_nop 0
	global_load_lds_dwordx4 v138, s[54:55]
	s_waitcnt vmcnt(6)
	s_waitcnt lgkmcnt(0)
	s_barrier
	s_setprio 1
	s_waitcnt lgkmcnt(0)
	v_mfma_i32_16x16x64_i8 v[62:65], v[90:93], v[196:199], v[62:65]
	v_mfma_i32_16x16x64_i8 v[58:61], v[172:175], v[196:199], v[58:61]
	v_mfma_i32_16x16x64_i8 v[46:49], v[90:93], v[204:207], v[46:49]
	v_mfma_i32_16x16x64_i8 v[42:45], v[172:175], v[204:207], v[42:45]
	v_mfma_i32_16x16x64_i8 v[30:33], v[90:93], v[212:215], v[30:33]
	v_mfma_i32_16x16x64_i8 v[26:29], v[172:175], v[212:215], v[26:29]
	v_mfma_i32_16x16x64_i8 v[14:17], v[90:93], v[220:223], v[14:17]
	v_mfma_i32_16x16x64_i8 v[10:13], v[172:175], v[220:223], v[10:13]
	v_mfma_i32_16x16x64_i8 v[62:65], v[98:101], v[200:203], v[62:65]
	v_mfma_i32_16x16x64_i8 v[58:61], v[176:179], v[200:203], v[58:61]
	v_mfma_i32_16x16x64_i8 v[46:49], v[98:101], v[208:211], v[46:49]
	v_mfma_i32_16x16x64_i8 v[42:45], v[176:179], v[208:211], v[42:45]
	v_mfma_i32_16x16x64_i8 v[30:33], v[98:101], v[216:219], v[30:33]
	v_mfma_i32_16x16x64_i8 v[26:29], v[176:179], v[216:219], v[26:29]
	v_mfma_i32_16x16x64_i8 v[14:17], v[98:101], v[224:227], v[14:17]
	v_mfma_i32_16x16x64_i8 v[10:13], v[176:179], v[224:227], v[10:13]
	s_setprio 0
	s_setprio 1
	v_mfma_i32_16x16x64_i8 v[54:57], v[180:183], v[196:199], v[54:57]
	v_mfma_i32_16x16x64_i8 v[50:53], v[188:191], v[196:199], v[50:53]
	v_mfma_i32_16x16x64_i8 v[38:41], v[180:183], v[204:207], v[38:41]
	v_mfma_i32_16x16x64_i8 v[34:37], v[188:191], v[204:207], v[34:37]
	v_mfma_i32_16x16x64_i8 v[22:25], v[180:183], v[212:215], v[22:25]
	v_mfma_i32_16x16x64_i8 v[18:21], v[188:191], v[212:215], v[18:21]
	v_mfma_i32_16x16x64_i8 v[6:9], v[180:183], v[220:223], v[6:9]
	v_mfma_i32_16x16x64_i8 v[2:5], v[188:191], v[220:223], v[2:5]
	v_mfma_i32_16x16x64_i8 v[54:57], v[184:187], v[200:203], v[54:57]
	v_mfma_i32_16x16x64_i8 v[50:53], v[192:195], v[200:203], v[50:53]
	v_mfma_i32_16x16x64_i8 v[38:41], v[184:187], v[208:211], v[38:41]
	v_mfma_i32_16x16x64_i8 v[34:37], v[192:195], v[208:211], v[34:37]
	v_mfma_i32_16x16x64_i8 v[22:25], v[184:187], v[216:219], v[22:25]
	v_mfma_i32_16x16x64_i8 v[18:21], v[192:195], v[216:219], v[18:21]
	v_mfma_i32_16x16x64_i8 v[6:9], v[184:187], v[224:227], v[6:9]
	v_mfma_i32_16x16x64_i8 v[2:5], v[192:195], v[224:227], v[2:5]
	s_setprio 0
	s_barrier
; #define PG8_STAGE(bufoff, gbase, voff) do { _Pragma("unroll") for (int _i = 0; _i < 2; ++_i) \
;         __builtin_amdgcn_global_load_lds((const unsigned*)((const char*)(gbase) + (voff)[_i]), (LAS unsigned*)(lds + (bufoff) + ldsw + _i * 8192), 16, 0, 0); } while (0)
; #define PG8_LDA(dst, b, h) do { _Pragma("unroll") for (int m = 0; m < 4; ++m) _Pragma("unroll") for (int k = 0; k < 2; ++k) dst[m][k] = *(const LAS bf16x8*)(lds + PG8_SA(b, h) + aoff + m * 2048 + k * 1024); } while (0)
; #define PG8_LDB(dst, b, h) do { _Pragma("unroll") for (int n = 0; n < 2; ++n) _Pragma("unroll") for (int k = 0; k < 2; ++k) dst[n][k] = *(const LAS bf16x8*)(lds + PG8_SB(b, h) + boff + n * 2048 + k * 1024); } while (0)
; #define PG8_WAIT_V(n) asm volatile("s_waitcnt vmcnt(" #n ")" ::: "memory")
; #define PG8_WAIT_L(n) asm volatile("s_waitcnt lgkmcnt(" #n ")" ::: "memory")
; #define PG8_BAR __builtin_amdgcn_s_barrier()
; #define PG8_SCHED __builtin_amdgcn_sched_barrier(0)
; template <class Epi, class Sched, bool I8 = false>
; __device__ __forceinline__ void gemm_phase(LAS unsigned char* lds, const Gemm g, const Sched& S, const Epi& E) {
;     ...
;             PG8_LDB(B0, 1, 0); PG8_LDB(B1, 1, 1); PG8_SCHED; PG8_LDA(At, 1, 0); PG8_STAGE(PG8_SA(0, 1), a2 + hstepA, voffA);
;             PG8_WAIT_V(8); PG8_WAIT_L(0); PG8_BAR; PG8_MMA(0, 0, At, B0); PG8_MMA(0, 1, At, B1); PG8_BAR; PG8_SCHED;
;             PG8_LDA(At, 1, 1); PG8_STAGE(PG8_SB(1, 0), b3, voffB); PG8_STAGE(PG8_SB(1, 1), b3 + hstepB, voffB); PG8_STAGE(PG8_SA(1, 0), a3, voffA);
;             PG8_WAIT_V(8); PG8_WAIT_L(0); PG8_BAR; PG8_MMA(1, 0, At, B0); PG8_MMA(1, 1, At, B1); PG8_BAR; PG8_SCHED;
;         }
	s_add_i32 s54, 0, 0x18000
	v_add_u32_e32 v146, s54, v165
	s_add_i32 s55, 0, 0x1c000
	ds_read_b128 v[90:93], v146
	ds_read_b128 v[98:101], v146 offset:1024
	ds_read_b128 v[172:175], v146 offset:2048
	ds_read_b128 v[176:179], v146 offset:3072
	v_add_u32_e32 v146, s55, v165
	ds_read_b128 v[180:183], v146
	ds_read_b128 v[184:187], v146 offset:1024
	ds_read_b128 v[188:191], v146 offset:2048
	ds_read_b128 v[192:195], v146 offset:3072
	s_mov_b32 m0, s36
	s_nop 0
	global_load_lds_dwordx4 v144, s[26:27]
	s_mov_b32 m0, s37
	s_nop 0
	global_load_lds_dwordx4 v140, s[26:27]
	s_add_u32 s26, s26, 0x4000
	s_addc_u32 s27, s27, 0
	s_mov_b32 m0, s38
	ds_read_b128 v[196:199], v171 offset:32768
	ds_read_b128 v[200:203], v171 offset:33792
	ds_read_b128 v[204:207], v171 offset:34816
	ds_read_b128 v[208:211], v171 offset:35840
	ds_read_b128 v[212:215], v171 offset:36864
	ds_read_b128 v[216:219], v171 offset:37888
	ds_read_b128 v[220:223], v171 offset:38912
	ds_read_b128 v[224:227], v171 offset:39936
	global_load_lds_dwordx4 v144, s[26:27]
	s_mov_b32 m0, s39
	s_nop 0
	global_load_lds_dwordx4 v140, s[26:27]
	s_waitcnt vmcnt(8)
	s_waitcnt lgkmcnt(0)
	s_barrier
	s_setprio 1
	s_waitcnt lgkmcnt(0)
	v_mfma_i32_16x16x64_i8 v[134:137], v[90:93], v[196:199], v[134:137]
	v_mfma_i32_16x16x64_i8 v[130:133], v[172:175], v[196:199], v[130:133]
	v_mfma_i32_16x16x64_i8 v[118:121], v[90:93], v[204:207], v[118:121]
	v_mfma_i32_16x16x64_i8 v[114:117], v[172:175], v[204:207], v[114:117]
	v_mfma_i32_16x16x64_i8 v[102:105], v[90:93], v[212:215], v[102:105]
	v_mfma_i32_16x16x64_i8 v[94:97], v[172:175], v[212:215], v[94:97]
	v_mfma_i32_16x16x64_i8 v[78:81], v[90:93], v[220:223], v[78:81]
	v_mfma_i32_16x16x64_i8 v[74:77], v[172:175], v[220:223], v[74:77]
	v_mfma_i32_16x16x64_i8 v[134:137], v[98:101], v[200:203], v[134:137]
	v_mfma_i32_16x16x64_i8 v[130:133], v[176:179], v[200:203], v[130:133]
	v_mfma_i32_16x16x64_i8 v[118:121], v[98:101], v[208:211], v[118:121]
	v_mfma_i32_16x16x64_i8 v[114:117], v[176:179], v[208:211], v[114:117]
	v_mfma_i32_16x16x64_i8 v[102:105], v[98:101], v[216:219], v[102:105]
	v_mfma_i32_16x16x64_i8 v[94:97], v[176:179], v[216:219], v[94:97]
	v_mfma_i32_16x16x64_i8 v[78:81], v[98:101], v[224:227], v[78:81]
	v_mfma_i32_16x16x64_i8 v[74:77], v[176:179], v[224:227], v[74:77]
	s_setprio 0
	s_setprio 1
	v_mfma_i32_16x16x64_i8 v[126:129], v[180:183], v[196:199], v[126:129]
	v_mfma_i32_16x16x64_i8 v[122:125], v[188:191], v[196:199], v[122:125]
	v_mfma_i32_16x16x64_i8 v[110:113], v[180:183], v[204:207], v[110:113]
	v_mfma_i32_16x16x64_i8 v[106:109], v[188:191], v[204:207], v[106:109]
	v_mfma_i32_16x16x64_i8 v[86:89], v[180:183], v[212:215], v[86:89]
	v_mfma_i32_16x16x64_i8 v[82:85], v[188:191], v[212:215], v[82:85]
	v_mfma_i32_16x16x64_i8 v[70:73], v[180:183], v[220:223], v[70:73]
	v_mfma_i32_16x16x64_i8 v[66:69], v[188:191], v[220:223], v[66:69]
	v_mfma_i32_16x16x64_i8 v[126:129], v[184:187], v[200:203], v[126:129]
	v_mfma_i32_16x16x64_i8 v[122:125], v[192:195], v[200:203], v[122:125]
	v_mfma_i32_16x16x64_i8 v[110:113], v[184:187], v[208:211], v[110:113]
	v_mfma_i32_16x16x64_i8 v[106:109], v[192:195], v[208:211], v[106:109]
	v_mfma_i32_16x16x64_i8 v[86:89], v[184:187], v[216:219], v[86:89]
	v_mfma_i32_16x16x64_i8 v[82:85], v[192:195], v[216:219], v[82:85]
	v_mfma_i32_16x16x64_i8 v[70:73], v[184:187], v[224:227], v[70:73]
	v_mfma_i32_16x16x64_i8 v[66:69], v[192:195], v[224:227], v[66:69]
	s_setprio 0
	s_barrier
	s_add_u32 s26, s24, 0x8000
	s_addc_u32 s27, s25, 0
	s_add_i32 s54, s54, s33
	s_mov_b32 m0, s54
	ds_read_b128 v[196:199], v171 offset:49152
	ds_read_b128 v[200:203], v171 offset:50176
	ds_read_b128 v[204:207], v171 offset:51200
	ds_read_b128 v[208:211], v171 offset:52224
	ds_read_b128 v[212:215], v171 offset:53248
	ds_read_b128 v[216:219], v171 offset:54272
	ds_read_b128 v[220:223], v171 offset:55296
	ds_read_b128 v[224:227], v171 offset:56320
	global_load_lds_dwordx4 v142, s[26:27]
	s_add_i32 m0, s54, 0x2000
	s_add_u32 s24, s24, 0xc000
	v_lshl_add_u64 v[158:159], s[26:27], 0, v[138:139]
	s_addc_u32 s25, s25, 0
	s_add_i32 s26, s55, s33
	global_load_lds_dwordx4 v[158:159], off
	s_mov_b32 m0, s26
	s_nop 0
	global_load_lds_dwordx4 v142, s[24:25]
	s_add_i32 m0, s26, 0x2000
	s_nop 0
	global_load_lds_dwordx4 v138, s[24:25]
	s_waitcnt vmcnt(6)
	s_waitcnt lgkmcnt(0)
	s_barrier
	s_setprio 1
	s_waitcnt lgkmcnt(0)
	v_mfma_i32_16x16x64_i8 v[62:65], v[90:93], v[196:199], v[62:65]
	v_mfma_i32_16x16x64_i8 v[58:61], v[172:175], v[196:199], v[58:61]
	v_mfma_i32_16x16x64_i8 v[46:49], v[90:93], v[204:207], v[46:49]
	v_mfma_i32_16x16x64_i8 v[42:45], v[172:175], v[204:207], v[42:45]
	v_mfma_i32_16x16x64_i8 v[30:33], v[90:93], v[212:215], v[30:33]
	v_mfma_i32_16x16x64_i8 v[26:29], v[172:175], v[212:215], v[26:29]
	v_mfma_i32_16x16x64_i8 v[14:17], v[90:93], v[220:223], v[14:17]
	v_mfma_i32_16x16x64_i8 v[10:13], v[172:175], v[220:223], v[10:13]
	v_mfma_i32_16x16x64_i8 v[62:65], v[98:101], v[200:203], v[62:65]
	v_mfma_i32_16x16x64_i8 v[58:61], v[176:179], v[200:203], v[58:61]
	v_mfma_i32_16x16x64_i8 v[46:49], v[98:101], v[208:211], v[46:49]
	v_mfma_i32_16x16x64_i8 v[42:45], v[176:179], v[208:211], v[42:45]
	v_mfma_i32_16x16x64_i8 v[30:33], v[98:101], v[216:219], v[30:33]
	v_mfma_i32_16x16x64_i8 v[26:29], v[176:179], v[216:219], v[26:29]
	v_mfma_i32_16x16x64_i8 v[14:17], v[98:101], v[224:227], v[14:17]
	v_mfma_i32_16x16x64_i8 v[10:13], v[176:179], v[224:227], v[10:13]
	s_setprio 0
	s_setprio 1
	v_mfma_i32_16x16x64_i8 v[54:57], v[180:183], v[196:199], v[54:57]
	v_mfma_i32_16x16x64_i8 v[50:53], v[188:191], v[196:199], v[50:53]
	v_mfma_i32_16x16x64_i8 v[38:41], v[180:183], v[204:207], v[38:41]
	v_mfma_i32_16x16x64_i8 v[34:37], v[188:191], v[204:207], v[34:37]
	v_mfma_i32_16x16x64_i8 v[22:25], v[180:183], v[212:215], v[22:25]
	v_mfma_i32_16x16x64_i8 v[18:21], v[188:191], v[212:215], v[18:21]
	v_mfma_i32_16x16x64_i8 v[6:9], v[180:183], v[220:223], v[6:9]
	v_mfma_i32_16x16x64_i8 v[2:5], v[188:191], v[220:223], v[2:5]
	v_mfma_i32_16x16x64_i8 v[54:57], v[184:187], v[200:203], v[54:57]
	v_mfma_i32_16x16x64_i8 v[50:53], v[192:195], v[200:203], v[50:53]
	v_mfma_i32_16x16x64_i8 v[38:41], v[184:187], v[208:211], v[38:41]
	v_mfma_i32_16x16x64_i8 v[34:37], v[192:195], v[208:211], v[34:37]
	v_mfma_i32_16x16x64_i8 v[22:25], v[184:187], v[216:219], v[22:25]
	v_mfma_i32_16x16x64_i8 v[18:21], v[192:195], v[216:219], v[18:21]
	v_mfma_i32_16x16x64_i8 v[6:9], v[184:187], v[224:227], v[6:9]
	v_mfma_i32_16x16x64_i8 v[2:5], v[192:195], v[224:227], v[2:5]
	s_setprio 0
	s_barrier
	s_add_i32 s53, s53, 2
	s_add_u32 s20, s20, 0x10000
	s_addc_u32 s21, s21, 0
	s_add_u32 s51, s51, 0x10000
	s_addc_u32 s52, s52, 0
	s_cmp_gt_u32 s53, 29
	s_cbranch_scc0 .LBB0_1169
	s_and_b64 vcc, exec, s[8:9]
	s_cbranch_vccz .LBB0_1172
	s_barrier

; #define PG8_STAGE(bufoff, gbase, voff) do { _Pragma("unroll") for (int _i = 0; _i < 2; ++_i) \
;         __builtin_amdgcn_global_load_lds((const unsigned*)((const char*)(gbase) + (voff)[_i]), (LAS unsigned*)(lds + (bufoff) + ldsw + _i * 8192), 16, 0, 0); } while (0)
; #define PG8_LDA(dst, b, h) do { _Pragma("unroll") for (int m = 0; m < 4; ++m) _Pragma("unroll") for (int k = 0; k < 2; ++k) dst[m][k] = *(const LAS bf16x8*)(lds + PG8_SA(b, h) + aoff + m * 2048 + k * 1024); } while (0)
; #define PG8_LDB(dst, b, h) do { _Pragma("unroll") for (int n = 0; n < 2; ++n) _Pragma("unroll") for (int k = 0; k < 2; ++k) dst[n][k] = *(const LAS bf16x8*)(lds + PG8_SB(b, h) + boff + n * 2048 + k * 1024); } while (0)
; #define PG8_WAIT_V(n) asm volatile("s_waitcnt vmcnt(" #n ")" ::: "memory")
; #define PG8_WAIT_L(n) asm volatile("s_waitcnt lgkmcnt(" #n ")" ::: "memory")
; #define PG8_BAR __builtin_amdgcn_s_barrier()
; #define PG8_SCHED __builtin_amdgcn_sched_barrier(0)
; template <class Epi, class Sched, bool I8 = false>
; __device__ __forceinline__ void gemm_phase(LAS unsigned char* lds, const Gemm g, const Sched& S, const Epi& E) {
;     ...
;         for (int t = 0; t < nt; t += 2) {
;             const bool last = (t == nt - 2);
;             const char* a1 = cA + (size_t)(t + 1) * kstep;
;             const char* a2 = last ? nA : cA + (size_t)(t + 2) * kstep; const char* b2 = last ? nB : cB + (size_t)(t + 2) * kstep;
;             const char* a3 = a2 + kstep; const char* b3 = b2 + kstep;
;             PG8_LDB(B0, 0, 0); PG8_LDB(B1, 0, 1); PG8_SCHED; PG8_LDA(At, 0, 0); PG8_STAGE(PG8_SA(1, 1), a1 + hstepA, voffA);
;             PG8_WAIT_V(8); PG8_WAIT_L(0); PG8_BAR; PG8_MMA(0, 0, At, B0); PG8_MMA(0, 1, At, B1); PG8_BAR; PG8_SCHED;
;             PG8_LDA(At, 0, 1); PG8_STAGE(PG8_SB(0, 0), b2, voffB); PG8_STAGE(PG8_SB(0, 1), b2 + hstepB, voffB); PG8_STAGE(PG8_SA(0, 0), a2, voffA);
;             PG8_WAIT_V(8); PG8_WAIT_L(0); PG8_BAR; PG8_MMA(1, 0, At, B0); PG8_MMA(1, 1, At, B1); PG8_BAR; PG8_SCHED;
.LBB0_1393:
	ds_read_b128 v[66:69], v180
	ds_read_b128 v[70:73], v180 offset:1024
	ds_read_b128 v[74:77], v180 offset:2048
	ds_read_b128 v[78:81], v180 offset:3072
	ds_read_b128 v[146:149], v181
	ds_read_b128 v[150:153], v181 offset:1024
	ds_read_b128 v[174:177], v181 offset:2048
	ds_read_b128 v[184:187], v181 offset:3072
	s_add_u32 s20, s18, 0x4000
	s_addc_u32 s21, s19, 0
	s_cmpk_eq_i32 s49, 0x52
	s_cselect_b32 s24, s0, s20
	s_cselect_b32 s25, s1, s21
	s_cselect_b32 s22, s16, s47
	s_cselect_b32 s23, s17, s48
	s_add_u32 s20, s24, 0x8000
	s_addc_u32 s21, s25, 0
	s_sub_u32 s98, s18, 0x4000
	s_subb_u32 s99, s19, 0
	s_mov_b32 m0, s37
	s_nop 0
	global_load_lds_dwordx4 v156, s[98:99]
	s_mov_b32 m0, s38
	s_nop 0
	global_load_lds_dwordx4 v160, s[98:99]
	s_add_i32 m0, s31, 0xc000
	ds_read_b128 v[188:191], v182
	ds_read_b128 v[192:195], v182 offset:1024
	ds_read_b128 v[196:199], v182 offset:2048
	ds_read_b128 v[200:203], v182 offset:3072
	ds_read_b128 v[204:207], v182 offset:4096
	ds_read_b128 v[208:211], v182 offset:5120
	ds_read_b128 v[212:215], v182 offset:6144
	ds_read_b128 v[216:219], v182 offset:7168
	global_load_lds_dwordx4 v166, s[18:19]
	s_add_i32 m0, s31, 0xe000
	s_nop 0
	global_load_lds_dwordx4 v168, s[18:19]
	s_waitcnt vmcnt(8)
	s_waitcnt lgkmcnt(0)
	s_barrier
	s_setprio 1
	s_waitcnt lgkmcnt(0)
	v_mfma_i32_16x16x64_i8 v[142:145], v[66:69], v[188:191], v[142:145]
	v_mfma_i32_16x16x64_i8 v[138:141], v[74:77], v[188:191], v[138:141]
	v_mfma_i32_16x16x64_i8 v[126:129], v[66:69], v[196:199], v[126:129]
	v_mfma_i32_16x16x64_i8 v[122:125], v[74:77], v[196:199], v[122:125]
	v_mfma_i32_16x16x64_i8 v[110:113], v[66:69], v[204:207], v[110:113]
	v_mfma_i32_16x16x64_i8 v[106:109], v[74:77], v[204:207], v[106:109]
	v_mfma_i32_16x16x64_i8 v[94:97], v[66:69], v[212:215], v[94:97]
	v_mfma_i32_16x16x64_i8 v[90:93], v[74:77], v[212:215], v[90:93]
	v_mfma_i32_16x16x64_i8 v[142:145], v[70:73], v[192:195], v[142:145]
	v_mfma_i32_16x16x64_i8 v[138:141], v[78:81], v[192:195], v[138:141]
	v_mfma_i32_16x16x64_i8 v[126:129], v[70:73], v[200:203], v[126:129]
	v_mfma_i32_16x16x64_i8 v[122:125], v[78:81], v[200:203], v[122:125]
	v_mfma_i32_16x16x64_i8 v[110:113], v[70:73], v[208:211], v[110:113]
	v_mfma_i32_16x16x64_i8 v[106:109], v[78:81], v[208:211], v[106:109]
	v_mfma_i32_16x16x64_i8 v[94:97], v[70:73], v[216:219], v[94:97]
	v_mfma_i32_16x16x64_i8 v[90:93], v[78:81], v[216:219], v[90:93]
	s_setprio 0
	s_setprio 1
	v_mfma_i32_16x16x64_i8 v[134:137], v[146:149], v[188:191], v[134:137]
	v_mfma_i32_16x16x64_i8 v[130:133], v[174:177], v[188:191], v[130:133]
	v_mfma_i32_16x16x64_i8 v[118:121], v[146:149], v[196:199], v[118:121]
	v_mfma_i32_16x16x64_i8 v[114:117], v[174:177], v[196:199], v[114:117]
	v_mfma_i32_16x16x64_i8 v[102:105], v[146:149], v[204:207], v[102:105]
	v_mfma_i32_16x16x64_i8 v[98:101], v[174:177], v[204:207], v[98:101]
	v_mfma_i32_16x16x64_i8 v[86:89], v[146:149], v[212:215], v[86:89]
	v_mfma_i32_16x16x64_i8 v[82:85], v[174:177], v[212:215], v[82:85]
	v_mfma_i32_16x16x64_i8 v[134:137], v[150:153], v[192:195], v[134:137]
	v_mfma_i32_16x16x64_i8 v[130:133], v[184:187], v[192:195], v[130:133]
	v_mfma_i32_16x16x64_i8 v[118:121], v[150:153], v[200:203], v[118:121]
	v_mfma_i32_16x16x64_i8 v[114:117], v[184:187], v[200:203], v[114:117]
	v_mfma_i32_16x16x64_i8 v[102:105], v[150:153], v[208:211], v[102:105]
	v_mfma_i32_16x16x64_i8 v[98:101], v[184:187], v[208:211], v[98:101]
	v_mfma_i32_16x16x64_i8 v[86:89], v[150:153], v[216:219], v[86:89]
	v_mfma_i32_16x16x64_i8 v[82:85], v[184:187], v[216:219], v[82:85]
	s_setprio 0
	s_barrier
	s_add_i32 s50, s41, s30
	s_mov_b32 m0, s50
	ds_read_b128 v[188:191], v182 offset:16384
	ds_read_b128 v[192:195], v182 offset:17408
	ds_read_b128 v[196:199], v182 offset:18432
	ds_read_b128 v[200:203], v182 offset:19456
	ds_read_b128 v[204:207], v182 offset:20480
	ds_read_b128 v[208:211], v182 offset:21504
	ds_read_b128 v[212:215], v182 offset:22528
	ds_read_b128 v[216:219], v182 offset:23552
	global_load_lds_dwordx4 v158, s[22:23]
	s_add_i32 m0, s50, 0x2000
	s_add_u32 s50, s22, 0x4000
	s_addc_u32 s51, s23, 0
	s_add_i32 s52, s42, s30
	global_load_lds_dwordx4 v162, s[22:23]
	s_mov_b32 m0, s52
	s_nop 0
	global_load_lds_dwordx4 v158, s[50:51]
	s_add_i32 m0, s52, 0x2000
	s_nop 0
	global_load_lds_dwordx4 v162, s[50:51]
	s_waitcnt vmcnt(6)
	s_waitcnt lgkmcnt(0)
	s_barrier
	s_setprio 1
	s_waitcnt lgkmcnt(0)
	v_mfma_i32_16x16x64_i8 v[62:65], v[66:69], v[188:191], v[62:65]
	v_mfma_i32_16x16x64_i8 v[58:61], v[74:77], v[188:191], v[58:61]
	v_mfma_i32_16x16x64_i8 v[46:49], v[66:69], v[196:199], v[46:49]
	v_mfma_i32_16x16x64_i8 v[42:45], v[74:77], v[196:199], v[42:45]
	v_mfma_i32_16x16x64_i8 v[30:33], v[66:69], v[204:207], v[30:33]
	v_mfma_i32_16x16x64_i8 v[26:29], v[74:77], v[204:207], v[26:29]
	v_mfma_i32_16x16x64_i8 v[14:17], v[66:69], v[212:215], v[14:17]
	v_mfma_i32_16x16x64_i8 v[10:13], v[74:77], v[212:215], v[10:13]
	v_mfma_i32_16x16x64_i8 v[62:65], v[70:73], v[192:195], v[62:65]
	v_mfma_i32_16x16x64_i8 v[58:61], v[78:81], v[192:195], v[58:61]
	v_mfma_i32_16x16x64_i8 v[46:49], v[70:73], v[200:203], v[46:49]
	v_mfma_i32_16x16x64_i8 v[42:45], v[78:81], v[200:203], v[42:45]
	v_mfma_i32_16x16x64_i8 v[30:33], v[70:73], v[208:211], v[30:33]
	v_mfma_i32_16x16x64_i8 v[26:29], v[78:81], v[208:211], v[26:29]
	v_mfma_i32_16x16x64_i8 v[14:17], v[70:73], v[216:219], v[14:17]
	v_mfma_i32_16x16x64_i8 v[10:13], v[78:81], v[216:219], v[10:13]
	s_setprio 0
	s_setprio 1
	v_mfma_i32_16x16x64_i8 v[54:57], v[146:149], v[188:191], v[54:57]
	v_mfma_i32_16x16x64_i8 v[50:53], v[174:177], v[188:191], v[50:53]
	v_mfma_i32_16x16x64_i8 v[38:41], v[146:149], v[196:199], v[38:41]
	v_mfma_i32_16x16x64_i8 v[34:37], v[174:177], v[196:199], v[34:37]
	v_mfma_i32_16x16x64_i8 v[22:25], v[146:149], v[204:207], v[22:25]
	v_mfma_i32_16x16x64_i8 v[18:21], v[174:177], v[204:207], v[18:21]
	v_mfma_i32_16x16x64_i8 v[6:9], v[146:149], v[212:215], v[6:9]
	v_mfma_i32_16x16x64_i8 v[2:5], v[174:177], v[212:215], v[2:5]
	v_mfma_i32_16x16x64_i8 v[54:57], v[150:153], v[192:195], v[54:57]
	v_mfma_i32_16x16x64_i8 v[50:53], v[184:187], v[192:195], v[50:53]
	v_mfma_i32_16x16x64_i8 v[38:41], v[150:153], v[200:203], v[38:41]
	v_mfma_i32_16x16x64_i8 v[34:37], v[184:187], v[200:203], v[34:37]
	v_mfma_i32_16x16x64_i8 v[22:25], v[150:153], v[208:211], v[22:25]
	v_mfma_i32_16x16x64_i8 v[18:21], v[184:187], v[208:211], v[18:21]
	v_mfma_i32_16x16x64_i8 v[6:9], v[150:153], v[216:219], v[6:9]
	v_mfma_i32_16x16x64_i8 v[2:5], v[184:187], v[216:219], v[2:5]
	s_setprio 0
	s_barrier
; #define PG8_STAGE(bufoff, gbase, voff) do { _Pragma("unroll") for (int _i = 0; _i < 2; ++_i) \
;         __builtin_amdgcn_global_load_lds((const unsigned*)((const char*)(gbase) + (voff)[_i]), (LAS unsigned*)(lds + (bufoff) + ldsw + _i * 8192), 16, 0, 0); } while (0)
; #define PG8_LDA(dst, b, h) do { _Pragma("unroll") for (int m = 0; m < 4; ++m) _Pragma("unroll") for (int k = 0; k < 2; ++k) dst[m][k] = *(const LAS bf16x8*)(lds + PG8_SA(b, h) + aoff + m * 2048 + k * 1024); } while (0)
; #define PG8_LDB(dst, b, h) do { _Pragma("unroll") for (int n = 0; n < 2; ++n) _Pragma("unroll") for (int k = 0; k < 2; ++k) dst[n][k] = *(const LAS bf16x8*)(lds + PG8_SB(b, h) + boff + n * 2048 + k * 1024); } while (0)
; #define PG8_WAIT_V(n) asm volatile("s_waitcnt vmcnt(" #n ")" ::: "memory")
; #define PG8_WAIT_L(n) asm volatile("s_waitcnt lgkmcnt(" #n ")" ::: "memory")
; #define PG8_BAR __builtin_amdgcn_s_barrier()
; #define PG8_SCHED __builtin_amdgcn_sched_barrier(0)
; template <class Epi, class Sched, bool I8 = false>
; __device__ __forceinline__ void gemm_phase(LAS unsigned char* lds, const Gemm g, const Sched& S, const Epi& E) {
;     ...
;             PG8_LDB(B0, 1, 0); PG8_LDB(B1, 1, 1); PG8_SCHED; PG8_LDA(At, 1, 0); PG8_STAGE(PG8_SA(0, 1), a2 + hstepA, voffA);
;             PG8_WAIT_V(8); PG8_WAIT_L(0); PG8_BAR; PG8_MMA(0, 0, At, B0); PG8_MMA(0, 1, At, B1); PG8_BAR; PG8_SCHED;
;             PG8_LDA(At, 1, 1); PG8_STAGE(PG8_SB(1, 0), b3, voffB); PG8_STAGE(PG8_SB(1, 1), b3 + hstepB, voffB); PG8_STAGE(PG8_SA(1, 0), a3, voffA);
;             PG8_WAIT_V(8); PG8_WAIT_L(0); PG8_BAR; PG8_MMA(1, 0, At, B0); PG8_MMA(1, 1, At, B1); PG8_BAR; PG8_SCHED;
;         }
	s_add_i32 s50, 0, 0x18000
	s_add_i32 s51, 0, 0x1c000
	v_add_u32_e32 v78, s50, v178
	v_add_u32_e32 v164, s51, v178
	ds_read_b128 v[66:69], v78
	ds_read_b128 v[70:73], v78 offset:1024
	ds_read_b128 v[74:77], v78 offset:2048
	ds_read_b128 v[78:81], v78 offset:3072
	ds_read_b128 v[146:149], v164
	ds_read_b128 v[150:153], v164 offset:1024
	ds_read_b128 v[174:177], v164 offset:2048
	ds_read_b128 v[184:187], v164 offset:3072
	s_mov_b32 m0, s31
	s_nop 0
	global_load_lds_dwordx4 v156, s[24:25]
	s_mov_b32 m0, s33
	s_nop 0
	global_load_lds_dwordx4 v160, s[24:25]
	s_add_u32 s24, s24, 0x4000
	s_addc_u32 s25, s25, 0
	s_mov_b32 m0, s34
	ds_read_b128 v[188:191], v182 offset:32768
	ds_read_b128 v[192:195], v182 offset:33792
	ds_read_b128 v[196:199], v182 offset:34816
	ds_read_b128 v[200:203], v182 offset:35840
	ds_read_b128 v[204:207], v182 offset:36864
	ds_read_b128 v[208:211], v182 offset:37888
	ds_read_b128 v[212:215], v182 offset:38912
	ds_read_b128 v[216:219], v182 offset:39936
	global_load_lds_dwordx4 v156, s[24:25]
	s_mov_b32 m0, s35
	s_nop 0
	global_load_lds_dwordx4 v160, s[24:25]
	s_waitcnt vmcnt(8)
	s_waitcnt lgkmcnt(0)
	s_barrier
	s_setprio 1
	s_waitcnt lgkmcnt(0)
	v_mfma_i32_16x16x64_i8 v[142:145], v[66:69], v[188:191], v[142:145]
	v_mfma_i32_16x16x64_i8 v[138:141], v[74:77], v[188:191], v[138:141]
	v_mfma_i32_16x16x64_i8 v[126:129], v[66:69], v[196:199], v[126:129]
	v_mfma_i32_16x16x64_i8 v[122:125], v[74:77], v[196:199], v[122:125]
	v_mfma_i32_16x16x64_i8 v[110:113], v[66:69], v[204:207], v[110:113]
	v_mfma_i32_16x16x64_i8 v[106:109], v[74:77], v[204:207], v[106:109]
	v_mfma_i32_16x16x64_i8 v[94:97], v[66:69], v[212:215], v[94:97]
	v_mfma_i32_16x16x64_i8 v[90:93], v[74:77], v[212:215], v[90:93]
	v_mfma_i32_16x16x64_i8 v[142:145], v[70:73], v[192:195], v[142:145]
	v_mfma_i32_16x16x64_i8 v[138:141], v[78:81], v[192:195], v[138:141]
	v_mfma_i32_16x16x64_i8 v[126:129], v[70:73], v[200:203], v[126:129]
	v_mfma_i32_16x16x64_i8 v[122:125], v[78:81], v[200:203], v[122:125]
	v_mfma_i32_16x16x64_i8 v[110:113], v[70:73], v[208:211], v[110:113]
	v_mfma_i32_16x16x64_i8 v[106:109], v[78:81], v[208:211], v[106:109]
	v_mfma_i32_16x16x64_i8 v[94:97], v[70:73], v[216:219], v[94:97]
	v_mfma_i32_16x16x64_i8 v[90:93], v[78:81], v[216:219], v[90:93]
	s_setprio 0
	s_setprio 1
	v_mfma_i32_16x16x64_i8 v[134:137], v[146:149], v[188:191], v[134:137]
	v_mfma_i32_16x16x64_i8 v[130:133], v[174:177], v[188:191], v[130:133]
	v_mfma_i32_16x16x64_i8 v[118:121], v[146:149], v[196:199], v[118:121]
	v_mfma_i32_16x16x64_i8 v[114:117], v[174:177], v[196:199], v[114:117]
	v_mfma_i32_16x16x64_i8 v[102:105], v[146:149], v[204:207], v[102:105]
	v_mfma_i32_16x16x64_i8 v[98:101], v[174:177], v[204:207], v[98:101]
	v_mfma_i32_16x16x64_i8 v[86:89], v[146:149], v[212:215], v[86:89]
	v_mfma_i32_16x16x64_i8 v[82:85], v[174:177], v[212:215], v[82:85]
	v_mfma_i32_16x16x64_i8 v[134:137], v[150:153], v[192:195], v[134:137]
	v_mfma_i32_16x16x64_i8 v[130:133], v[184:187], v[192:195], v[130:133]
	v_mfma_i32_16x16x64_i8 v[118:121], v[150:153], v[200:203], v[118:121]
	v_mfma_i32_16x16x64_i8 v[114:117], v[184:187], v[200:203], v[114:117]
	v_mfma_i32_16x16x64_i8 v[102:105], v[150:153], v[208:211], v[102:105]
	v_mfma_i32_16x16x64_i8 v[98:101], v[184:187], v[208:211], v[98:101]
	v_mfma_i32_16x16x64_i8 v[86:89], v[150:153], v[216:219], v[86:89]
	v_mfma_i32_16x16x64_i8 v[82:85], v[184:187], v[216:219], v[82:85]
	s_setprio 0
	s_barrier
	s_add_u32 s24, s22, 0x8000
	s_addc_u32 s25, s23, 0
	s_add_i32 s50, s50, s30
	s_mov_b32 m0, s50
	ds_read_b128 v[188:191], v182 offset:49152
	ds_read_b128 v[192:195], v182 offset:50176
	ds_read_b128 v[196:199], v182 offset:51200
	ds_read_b128 v[200:203], v182 offset:52224
	ds_read_b128 v[204:207], v182 offset:53248
	ds_read_b128 v[208:211], v182 offset:54272
	ds_read_b128 v[212:215], v182 offset:55296
	ds_read_b128 v[216:219], v182 offset:56320
	global_load_lds_dwordx4 v158, s[24:25]
	s_add_i32 m0, s50, 0x2000
	s_add_u32 s22, s22, 0xc000
	v_lshl_add_u64 v[220:221], s[24:25], 0, v[162:163]
	s_addc_u32 s23, s23, 0
	s_add_i32 s24, s51, s30
	global_load_lds_dwordx4 v[220:221], off
	s_mov_b32 m0, s24
	s_nop 0
	global_load_lds_dwordx4 v158, s[22:23]
	s_add_i32 m0, s24, 0x2000
	s_nop 0
	global_load_lds_dwordx4 v162, s[22:23]
	s_waitcnt vmcnt(6)
	s_waitcnt lgkmcnt(0)
	s_barrier
	s_setprio 1
	s_waitcnt lgkmcnt(0)
	v_mfma_i32_16x16x64_i8 v[62:65], v[66:69], v[188:191], v[62:65]
	v_mfma_i32_16x16x64_i8 v[58:61], v[74:77], v[188:191], v[58:61]
	v_mfma_i32_16x16x64_i8 v[46:49], v[66:69], v[196:199], v[46:49]
	v_mfma_i32_16x16x64_i8 v[42:45], v[74:77], v[196:199], v[42:45]
	v_mfma_i32_16x16x64_i8 v[30:33], v[66:69], v[204:207], v[30:33]
	v_mfma_i32_16x16x64_i8 v[26:29], v[74:77], v[204:207], v[26:29]
	v_mfma_i32_16x16x64_i8 v[14:17], v[66:69], v[212:215], v[14:17]
	v_mfma_i32_16x16x64_i8 v[10:13], v[74:77], v[212:215], v[10:13]
	v_mfma_i32_16x16x64_i8 v[62:65], v[70:73], v[192:195], v[62:65]
	v_mfma_i32_16x16x64_i8 v[58:61], v[78:81], v[192:195], v[58:61]
	v_mfma_i32_16x16x64_i8 v[46:49], v[70:73], v[200:203], v[46:49]
	v_mfma_i32_16x16x64_i8 v[42:45], v[78:81], v[200:203], v[42:45]
	v_mfma_i32_16x16x64_i8 v[30:33], v[70:73], v[208:211], v[30:33]
	v_mfma_i32_16x16x64_i8 v[26:29], v[78:81], v[208:211], v[26:29]
	v_mfma_i32_16x16x64_i8 v[14:17], v[70:73], v[216:219], v[14:17]
	v_mfma_i32_16x16x64_i8 v[10:13], v[78:81], v[216:219], v[10:13]
	s_setprio 0
	s_setprio 1
	v_mfma_i32_16x16x64_i8 v[54:57], v[146:149], v[188:191], v[54:57]
	v_mfma_i32_16x16x64_i8 v[50:53], v[174:177], v[188:191], v[50:53]
	v_mfma_i32_16x16x64_i8 v[38:41], v[146:149], v[196:199], v[38:41]
	v_mfma_i32_16x16x64_i8 v[34:37], v[174:177], v[196:199], v[34:37]
	v_mfma_i32_16x16x64_i8 v[22:25], v[146:149], v[204:207], v[22:25]
	v_mfma_i32_16x16x64_i8 v[18:21], v[174:177], v[204:207], v[18:21]
	v_mfma_i32_16x16x64_i8 v[6:9], v[146:149], v[212:215], v[6:9]
	v_mfma_i32_16x16x64_i8 v[2:5], v[174:177], v[212:215], v[2:5]
	v_mfma_i32_16x16x64_i8 v[54:57], v[150:153], v[192:195], v[54:57]
	v_mfma_i32_16x16x64_i8 v[50:53], v[184:187], v[192:195], v[50:53]
	v_mfma_i32_16x16x64_i8 v[38:41], v[150:153], v[200:203], v[38:41]
	v_mfma_i32_16x16x64_i8 v[34:37], v[184:187], v[200:203], v[34:37]
	v_mfma_i32_16x16x64_i8 v[22:25], v[150:153], v[208:211], v[22:25]
	v_mfma_i32_16x16x64_i8 v[18:21], v[184:187], v[208:211], v[18:21]
	v_mfma_i32_16x16x64_i8 v[6:9], v[150:153], v[216:219], v[6:9]
	v_mfma_i32_16x16x64_i8 v[2:5], v[184:187], v[216:219], v[2:5]
	s_setprio 0
	s_barrier
	s_add_i32 s49, s49, 2
	s_add_u32 s18, s18, 0x10000
	s_addc_u32 s19, s19, 0
	s_add_u32 s47, s47, 0x10000
	s_addc_u32 s48, s48, 0
	s_cmpk_gt_u32 s49, 0x53
	s_cbranch_scc0 .LBB0_1393
	s_and_b64 vcc, exec, s[14:15]
	s_cbranch_vccz .LBB0_1396
	s_barrier

; #define PG8_STAGE(bufoff, gbase, voff) do { _Pragma("unroll") for (int _i = 0; _i < 2; ++_i) \
;         __builtin_amdgcn_global_load_lds((const unsigned*)((const char*)(gbase) + (voff)[_i]), (LAS unsigned*)(lds + (bufoff) + ldsw + _i * 8192), 16, 0, 0); } while (0)
; #define PG8_LDA(dst, b, h) do { _Pragma("unroll") for (int m = 0; m < 4; ++m) _Pragma("unroll") for (int k = 0; k < 2; ++k) dst[m][k] = *(const LAS bf16x8*)(lds + PG8_SA(b, h) + aoff + m * 2048 + k * 1024); } while (0)
; #define PG8_LDB(dst, b, h) do { _Pragma("unroll") for (int n = 0; n < 2; ++n) _Pragma("unroll") for (int k = 0; k < 2; ++k) dst[n][k] = *(const LAS bf16x8*)(lds + PG8_SB(b, h) + boff + n * 2048 + k * 1024); } while (0)
; #define PG8_WAIT_V(n) asm volatile("s_waitcnt vmcnt(" #n ")" ::: "memory")
; #define PG8_WAIT_L(n) asm volatile("s_waitcnt lgkmcnt(" #n ")" ::: "memory")
; #define PG8_BAR __builtin_amdgcn_s_barrier()
; #define PG8_SCHED __builtin_amdgcn_sched_barrier(0)
; template <class Epi, class Sched, bool I8 = false>
; __device__ __forceinline__ void gemm_phase(LAS unsigned char* lds, const Gemm g, const Sched& S, const Epi& E) {
;     ...
;         for (int t = 0; t < nt; t += 2) {
;             const bool last = (t == nt - 2);
;             const char* a1 = cA + (size_t)(t + 1) * kstep;
;             const char* a2 = last ? nA : cA + (size_t)(t + 2) * kstep; const char* b2 = last ? nB : cB + (size_t)(t + 2) * kstep;
;             const char* a3 = a2 + kstep; const char* b3 = b2 + kstep;
;             PG8_LDB(B0, 0, 0); PG8_LDB(B1, 0, 1); PG8_SCHED; PG8_LDA(At, 0, 0); PG8_STAGE(PG8_SA(1, 1), a1 + hstepA, voffA);
;             PG8_WAIT_V(8); PG8_WAIT_L(0); PG8_BAR; PG8_MMA(0, 0, At, B0); PG8_MMA(0, 1, At, B1); PG8_BAR; PG8_SCHED;
;             PG8_LDA(At, 0, 1); PG8_STAGE(PG8_SB(0, 0), b2, voffB); PG8_STAGE(PG8_SB(0, 1), b2 + hstepB, voffB); PG8_STAGE(PG8_SA(0, 0), a2, voffA);
;             PG8_WAIT_V(8); PG8_WAIT_L(0); PG8_BAR; PG8_MMA(1, 0, At, B0); PG8_MMA(1, 1, At, B1); PG8_BAR; PG8_SCHED;
.LBB0_1482:
	ds_read_b128 v[152:155], v182
	ds_read_b128 v[156:159], v182 offset:1024
	ds_read_b128 v[160:163], v182 offset:2048
	ds_read_b128 v[164:167], v182 offset:3072
	ds_read_b128 v[168:171], v183
	ds_read_b128 v[172:175], v183 offset:1024
	ds_read_b128 v[176:179], v183 offset:2048
	ds_read_b128 v[186:189], v183 offset:3072
	s_add_u32 s38, s8, 0x4000
	s_addc_u32 s39, s9, 0
	s_cmp_eq_u32 s47, 60
	s_cselect_b32 s42, s31, s38
	s_cselect_b32 s43, s7, s39
	s_cselect_b32 s40, s44, s45
	s_cselect_b32 s41, s29, s46
	s_add_u32 s38, s42, 0x8000
	s_addc_u32 s39, s43, 0
	s_sub_u32 s98, s8, 0x4000
	s_subb_u32 s99, s9, 0
	s_mov_b32 m0, s58
	s_nop 0
	global_load_lds_dwordx4 v130, s[98:99]
	s_mov_b32 m0, s59
	s_nop 0
	global_load_lds_dwordx4 v134, s[98:99]
	s_add_i32 m0, s33, 0xc000
	ds_read_b128 v[190:193], v184
	ds_read_b128 v[194:197], v184 offset:1024
	ds_read_b128 v[198:201], v184 offset:2048
	ds_read_b128 v[202:205], v184 offset:3072
	ds_read_b128 v[206:209], v184 offset:4096
	ds_read_b128 v[210:213], v184 offset:5120
	ds_read_b128 v[214:217], v184 offset:6144
	ds_read_b128 v[218:221], v184 offset:7168
	global_load_lds_dwordx4 v144, s[8:9]
	s_add_i32 m0, s33, 0xe000
	s_nop 0
	global_load_lds_dwordx4 v146, s[8:9]
	s_waitcnt vmcnt(8)
	s_waitcnt lgkmcnt(0)
	s_barrier
	s_setprio 1
	s_waitcnt lgkmcnt(0)
	v_mfma_f32_16x16x32_bf16 v[126:129], v[152:155], v[190:193], v[126:129]
	v_mfma_f32_16x16x32_bf16 v[122:125], v[160:163], v[190:193], v[122:125]
	v_mfma_f32_16x16x32_bf16 v[110:113], v[152:155], v[198:201], v[110:113]
	v_mfma_f32_16x16x32_bf16 v[106:109], v[160:163], v[198:201], v[106:109]
	v_mfma_f32_16x16x32_bf16 v[94:97], v[152:155], v[206:209], v[94:97]
	v_mfma_f32_16x16x32_bf16 v[90:93], v[160:163], v[206:209], v[90:93]
	v_mfma_f32_16x16x32_bf16 v[78:81], v[152:155], v[214:217], v[78:81]
	v_mfma_f32_16x16x32_bf16 v[74:77], v[160:163], v[214:217], v[74:77]
	v_mfma_f32_16x16x32_bf16 v[126:129], v[156:159], v[194:197], v[126:129]
	v_mfma_f32_16x16x32_bf16 v[122:125], v[164:167], v[194:197], v[122:125]
	v_mfma_f32_16x16x32_bf16 v[110:113], v[156:159], v[202:205], v[110:113]
	v_mfma_f32_16x16x32_bf16 v[106:109], v[164:167], v[202:205], v[106:109]
	v_mfma_f32_16x16x32_bf16 v[94:97], v[156:159], v[210:213], v[94:97]
	v_mfma_f32_16x16x32_bf16 v[90:93], v[164:167], v[210:213], v[90:93]
	v_mfma_f32_16x16x32_bf16 v[78:81], v[156:159], v[218:221], v[78:81]
	v_mfma_f32_16x16x32_bf16 v[74:77], v[164:167], v[218:221], v[74:77]
	s_setprio 0
	s_setprio 1
	v_mfma_f32_16x16x32_bf16 v[118:121], v[168:171], v[190:193], v[118:121]
	v_mfma_f32_16x16x32_bf16 v[114:117], v[176:179], v[190:193], v[114:117]
	v_mfma_f32_16x16x32_bf16 v[102:105], v[168:171], v[198:201], v[102:105]
	v_mfma_f32_16x16x32_bf16 v[98:101], v[176:179], v[198:201], v[98:101]
	v_mfma_f32_16x16x32_bf16 v[86:89], v[168:171], v[206:209], v[86:89]
	v_mfma_f32_16x16x32_bf16 v[82:85], v[176:179], v[206:209], v[82:85]
	v_mfma_f32_16x16x32_bf16 v[70:73], v[168:171], v[214:217], v[70:73]
	v_mfma_f32_16x16x32_bf16 v[66:69], v[176:179], v[214:217], v[66:69]
	v_mfma_f32_16x16x32_bf16 v[118:121], v[172:175], v[194:197], v[118:121]
	v_mfma_f32_16x16x32_bf16 v[114:117], v[186:189], v[194:197], v[114:117]
	v_mfma_f32_16x16x32_bf16 v[102:105], v[172:175], v[202:205], v[102:105]
	v_mfma_f32_16x16x32_bf16 v[98:101], v[186:189], v[202:205], v[98:101]
	v_mfma_f32_16x16x32_bf16 v[86:89], v[172:175], v[210:213], v[86:89]
	v_mfma_f32_16x16x32_bf16 v[82:85], v[186:189], v[210:213], v[82:85]
	v_mfma_f32_16x16x32_bf16 v[70:73], v[172:175], v[218:221], v[70:73]
	v_mfma_f32_16x16x32_bf16 v[66:69], v[186:189], v[218:221], v[66:69]
	s_setprio 0
	s_barrier
	s_add_i32 s48, s63, s25
	s_mov_b32 m0, s48
	ds_read_b128 v[190:193], v184 offset:16384
	ds_read_b128 v[194:197], v184 offset:17408
	ds_read_b128 v[198:201], v184 offset:18432
	ds_read_b128 v[202:205], v184 offset:19456
	ds_read_b128 v[206:209], v184 offset:20480
	ds_read_b128 v[210:213], v184 offset:21504
	ds_read_b128 v[214:217], v184 offset:22528
	ds_read_b128 v[218:221], v184 offset:23552
	global_load_lds_dwordx4 v132, s[40:41]
	s_add_i32 m0, s48, 0x2000
	s_add_u32 s48, s40, 0x4000
	s_addc_u32 s49, s41, 0
	s_add_i32 s50, s64, s25
	global_load_lds_dwordx4 v136, s[40:41]
	s_mov_b32 m0, s50
	s_nop 0
	global_load_lds_dwordx4 v132, s[48:49]
	s_add_i32 m0, s50, 0x2000
	s_nop 0
	global_load_lds_dwordx4 v136, s[48:49]
	s_waitcnt vmcnt(6)
	s_waitcnt lgkmcnt(0)
	s_barrier
	s_setprio 1
	s_waitcnt lgkmcnt(0)
	v_mfma_f32_16x16x32_bf16 v[62:65], v[152:155], v[190:193], v[62:65]
	v_mfma_f32_16x16x32_bf16 v[58:61], v[160:163], v[190:193], v[58:61]
	v_mfma_f32_16x16x32_bf16 v[46:49], v[152:155], v[198:201], v[46:49]
	v_mfma_f32_16x16x32_bf16 v[42:45], v[160:163], v[198:201], v[42:45]
	v_mfma_f32_16x16x32_bf16 v[30:33], v[152:155], v[206:209], v[30:33]
	v_mfma_f32_16x16x32_bf16 v[26:29], v[160:163], v[206:209], v[26:29]
	v_mfma_f32_16x16x32_bf16 v[14:17], v[152:155], v[214:217], v[14:17]
	v_mfma_f32_16x16x32_bf16 v[10:13], v[160:163], v[214:217], v[10:13]
	v_mfma_f32_16x16x32_bf16 v[62:65], v[156:159], v[194:197], v[62:65]
	v_mfma_f32_16x16x32_bf16 v[58:61], v[164:167], v[194:197], v[58:61]
	v_mfma_f32_16x16x32_bf16 v[46:49], v[156:159], v[202:205], v[46:49]
	v_mfma_f32_16x16x32_bf16 v[42:45], v[164:167], v[202:205], v[42:45]
	v_mfma_f32_16x16x32_bf16 v[30:33], v[156:159], v[210:213], v[30:33]
	v_mfma_f32_16x16x32_bf16 v[26:29], v[164:167], v[210:213], v[26:29]
	v_mfma_f32_16x16x32_bf16 v[14:17], v[156:159], v[218:221], v[14:17]
	v_mfma_f32_16x16x32_bf16 v[10:13], v[164:167], v[218:221], v[10:13]
	s_setprio 0
	s_setprio 1
	v_mfma_f32_16x16x32_bf16 v[54:57], v[168:171], v[190:193], v[54:57]
	v_mfma_f32_16x16x32_bf16 v[50:53], v[176:179], v[190:193], v[50:53]
	v_mfma_f32_16x16x32_bf16 v[38:41], v[168:171], v[198:201], v[38:41]
	v_mfma_f32_16x16x32_bf16 v[34:37], v[176:179], v[198:201], v[34:37]
	v_mfma_f32_16x16x32_bf16 v[22:25], v[168:171], v[206:209], v[22:25]
	v_mfma_f32_16x16x32_bf16 v[18:21], v[176:179], v[206:209], v[18:21]
	v_mfma_f32_16x16x32_bf16 v[6:9], v[168:171], v[214:217], v[6:9]
	v_mfma_f32_16x16x32_bf16 v[2:5], v[176:179], v[214:217], v[2:5]
	v_mfma_f32_16x16x32_bf16 v[54:57], v[172:175], v[194:197], v[54:57]
	v_mfma_f32_16x16x32_bf16 v[50:53], v[186:189], v[194:197], v[50:53]
	v_mfma_f32_16x16x32_bf16 v[38:41], v[172:175], v[202:205], v[38:41]
	v_mfma_f32_16x16x32_bf16 v[34:37], v[186:189], v[202:205], v[34:37]
	v_mfma_f32_16x16x32_bf16 v[22:25], v[172:175], v[210:213], v[22:25]
	v_mfma_f32_16x16x32_bf16 v[18:21], v[186:189], v[210:213], v[18:21]
	v_mfma_f32_16x16x32_bf16 v[6:9], v[172:175], v[218:221], v[6:9]
	v_mfma_f32_16x16x32_bf16 v[2:5], v[186:189], v[218:221], v[2:5]
	s_setprio 0
	s_barrier
; #define PG8_STAGE(bufoff, gbase, voff) do { _Pragma("unroll") for (int _i = 0; _i < 2; ++_i) \
;         __builtin_amdgcn_global_load_lds((const unsigned*)((const char*)(gbase) + (voff)[_i]), (LAS unsigned*)(lds + (bufoff) + ldsw + _i * 8192), 16, 0, 0); } while (0)
; #define PG8_LDA(dst, b, h) do { _Pragma("unroll") for (int m = 0; m < 4; ++m) _Pragma("unroll") for (int k = 0; k < 2; ++k) dst[m][k] = *(const LAS bf16x8*)(lds + PG8_SA(b, h) + aoff + m * 2048 + k * 1024); } while (0)
; #define PG8_LDB(dst, b, h) do { _Pragma("unroll") for (int n = 0; n < 2; ++n) _Pragma("unroll") for (int k = 0; k < 2; ++k) dst[n][k] = *(const LAS bf16x8*)(lds + PG8_SB(b, h) + boff + n * 2048 + k * 1024); } while (0)
; #define PG8_WAIT_V(n) asm volatile("s_waitcnt vmcnt(" #n ")" ::: "memory")
; #define PG8_WAIT_L(n) asm volatile("s_waitcnt lgkmcnt(" #n ")" ::: "memory")
; #define PG8_BAR __builtin_amdgcn_s_barrier()
; #define PG8_SCHED __builtin_amdgcn_sched_barrier(0)
; template <class Epi, class Sched, bool I8 = false>
; __device__ __forceinline__ void gemm_phase(LAS unsigned char* lds, const Gemm g, const Sched& S, const Epi& E) {
;     ...
;             PG8_LDB(B0, 1, 0); PG8_LDB(B1, 1, 1); PG8_SCHED; PG8_LDA(At, 1, 0); PG8_STAGE(PG8_SA(0, 1), a2 + hstepA, voffA);
;             PG8_WAIT_V(8); PG8_WAIT_L(0); PG8_BAR; PG8_MMA(0, 0, At, B0); PG8_MMA(0, 1, At, B1); PG8_BAR; PG8_SCHED;
;             PG8_LDA(At, 1, 1); PG8_STAGE(PG8_SB(1, 0), b3, voffB); PG8_STAGE(PG8_SB(1, 1), b3 + hstepB, voffB); PG8_STAGE(PG8_SA(1, 0), a3, voffA);
;             PG8_WAIT_V(8); PG8_WAIT_L(0); PG8_BAR; PG8_MMA(1, 0, At, B0); PG8_MMA(1, 1, At, B1); PG8_BAR; PG8_SCHED;
;         }
	s_add_i32 s48, 0, 0x18000
	v_add_u32_e32 v138, s48, v181
	s_add_i32 s49, 0, 0x1c000
	ds_read_b128 v[152:155], v138
	ds_read_b128 v[156:159], v138 offset:1024
	ds_read_b128 v[160:163], v138 offset:2048
	ds_read_b128 v[164:167], v138 offset:3072
	v_add_u32_e32 v138, s49, v181
	ds_read_b128 v[168:171], v138
	ds_read_b128 v[172:175], v138 offset:1024
	ds_read_b128 v[176:179], v138 offset:2048
	ds_read_b128 v[186:189], v138 offset:3072
	s_mov_b32 m0, s33
	s_nop 0
	global_load_lds_dwordx4 v130, s[42:43]
	s_mov_b32 m0, s52
	s_nop 0
	global_load_lds_dwordx4 v134, s[42:43]
	s_add_u32 s42, s42, 0x4000
	s_addc_u32 s43, s43, 0
	s_mov_b32 m0, s53
	ds_read_b128 v[190:193], v184 offset:32768
	ds_read_b128 v[194:197], v184 offset:33792
	ds_read_b128 v[198:201], v184 offset:34816
	ds_read_b128 v[202:205], v184 offset:35840
	ds_read_b128 v[206:209], v184 offset:36864
	ds_read_b128 v[210:213], v184 offset:37888
	ds_read_b128 v[214:217], v184 offset:38912
	ds_read_b128 v[218:221], v184 offset:39936
	global_load_lds_dwordx4 v130, s[42:43]
	s_mov_b32 m0, s54
	s_nop 0
	global_load_lds_dwordx4 v134, s[42:43]
	s_waitcnt vmcnt(8)
	s_waitcnt lgkmcnt(0)
	s_barrier
	s_setprio 1
	s_waitcnt lgkmcnt(0)
	v_mfma_f32_16x16x32_bf16 v[126:129], v[152:155], v[190:193], v[126:129]
	v_mfma_f32_16x16x32_bf16 v[122:125], v[160:163], v[190:193], v[122:125]
	v_mfma_f32_16x16x32_bf16 v[110:113], v[152:155], v[198:201], v[110:113]
	v_mfma_f32_16x16x32_bf16 v[106:109], v[160:163], v[198:201], v[106:109]
	v_mfma_f32_16x16x32_bf16 v[94:97], v[152:155], v[206:209], v[94:97]
	v_mfma_f32_16x16x32_bf16 v[90:93], v[160:163], v[206:209], v[90:93]
	v_mfma_f32_16x16x32_bf16 v[78:81], v[152:155], v[214:217], v[78:81]
	v_mfma_f32_16x16x32_bf16 v[74:77], v[160:163], v[214:217], v[74:77]
	v_mfma_f32_16x16x32_bf16 v[126:129], v[156:159], v[194:197], v[126:129]
	v_mfma_f32_16x16x32_bf16 v[122:125], v[164:167], v[194:197], v[122:125]
	v_mfma_f32_16x16x32_bf16 v[110:113], v[156:159], v[202:205], v[110:113]
	v_mfma_f32_16x16x32_bf16 v[106:109], v[164:167], v[202:205], v[106:109]
	v_mfma_f32_16x16x32_bf16 v[94:97], v[156:159], v[210:213], v[94:97]
	v_mfma_f32_16x16x32_bf16 v[90:93], v[164:167], v[210:213], v[90:93]
	v_mfma_f32_16x16x32_bf16 v[78:81], v[156:159], v[218:221], v[78:81]
	v_mfma_f32_16x16x32_bf16 v[74:77], v[164:167], v[218:221], v[74:77]
	s_setprio 0
	s_setprio 1
	v_mfma_f32_16x16x32_bf16 v[118:121], v[168:171], v[190:193], v[118:121]
	v_mfma_f32_16x16x32_bf16 v[114:117], v[176:179], v[190:193], v[114:117]
	v_mfma_f32_16x16x32_bf16 v[102:105], v[168:171], v[198:201], v[102:105]
	v_mfma_f32_16x16x32_bf16 v[98:101], v[176:179], v[198:201], v[98:101]
	v_mfma_f32_16x16x32_bf16 v[86:89], v[168:171], v[206:209], v[86:89]
	v_mfma_f32_16x16x32_bf16 v[82:85], v[176:179], v[206:209], v[82:85]
	v_mfma_f32_16x16x32_bf16 v[70:73], v[168:171], v[214:217], v[70:73]
	v_mfma_f32_16x16x32_bf16 v[66:69], v[176:179], v[214:217], v[66:69]
	v_mfma_f32_16x16x32_bf16 v[118:121], v[172:175], v[194:197], v[118:121]
	v_mfma_f32_16x16x32_bf16 v[114:117], v[186:189], v[194:197], v[114:117]
	v_mfma_f32_16x16x32_bf16 v[102:105], v[172:175], v[202:205], v[102:105]
	v_mfma_f32_16x16x32_bf16 v[98:101], v[186:189], v[202:205], v[98:101]
	v_mfma_f32_16x16x32_bf16 v[86:89], v[172:175], v[210:213], v[86:89]
	v_mfma_f32_16x16x32_bf16 v[82:85], v[186:189], v[210:213], v[82:85]
	v_mfma_f32_16x16x32_bf16 v[70:73], v[172:175], v[218:221], v[70:73]
	v_mfma_f32_16x16x32_bf16 v[66:69], v[186:189], v[218:221], v[66:69]
	s_setprio 0
	s_barrier
	s_add_u32 s42, s40, 0x8000
	s_addc_u32 s43, s41, 0
	s_add_i32 s48, s48, s25
	s_mov_b32 m0, s48
	ds_read_b128 v[190:193], v184 offset:49152
	ds_read_b128 v[194:197], v184 offset:50176
	ds_read_b128 v[198:201], v184 offset:51200
	ds_read_b128 v[202:205], v184 offset:52224
	ds_read_b128 v[206:209], v184 offset:53248
	ds_read_b128 v[210:213], v184 offset:54272
	ds_read_b128 v[214:217], v184 offset:55296
	ds_read_b128 v[218:221], v184 offset:56320
	global_load_lds_dwordx4 v132, s[42:43]
	s_add_i32 m0, s48, 0x2000
	s_add_u32 s40, s40, 0xc000
	v_lshl_add_u64 v[222:223], s[42:43], 0, v[136:137]
	s_addc_u32 s41, s41, 0
	s_add_i32 s42, s49, s25
	global_load_lds_dwordx4 v[222:223], off
	s_mov_b32 m0, s42
	s_nop 0
	global_load_lds_dwordx4 v132, s[40:41]
	s_add_i32 m0, s42, 0x2000
	s_nop 0
	global_load_lds_dwordx4 v136, s[40:41]
	s_waitcnt vmcnt(6)
	s_waitcnt lgkmcnt(0)
	s_barrier
	s_setprio 1
	s_waitcnt lgkmcnt(0)
	v_mfma_f32_16x16x32_bf16 v[62:65], v[152:155], v[190:193], v[62:65]
	v_mfma_f32_16x16x32_bf16 v[58:61], v[160:163], v[190:193], v[58:61]
	v_mfma_f32_16x16x32_bf16 v[46:49], v[152:155], v[198:201], v[46:49]
	v_mfma_f32_16x16x32_bf16 v[42:45], v[160:163], v[198:201], v[42:45]
	v_mfma_f32_16x16x32_bf16 v[30:33], v[152:155], v[206:209], v[30:33]
	v_mfma_f32_16x16x32_bf16 v[26:29], v[160:163], v[206:209], v[26:29]
	v_mfma_f32_16x16x32_bf16 v[14:17], v[152:155], v[214:217], v[14:17]
	v_mfma_f32_16x16x32_bf16 v[10:13], v[160:163], v[214:217], v[10:13]
	v_mfma_f32_16x16x32_bf16 v[62:65], v[156:159], v[194:197], v[62:65]
	v_mfma_f32_16x16x32_bf16 v[58:61], v[164:167], v[194:197], v[58:61]
	v_mfma_f32_16x16x32_bf16 v[46:49], v[156:159], v[202:205], v[46:49]
	v_mfma_f32_16x16x32_bf16 v[42:45], v[164:167], v[202:205], v[42:45]
	v_mfma_f32_16x16x32_bf16 v[30:33], v[156:159], v[210:213], v[30:33]
	v_mfma_f32_16x16x32_bf16 v[26:29], v[164:167], v[210:213], v[26:29]
	v_mfma_f32_16x16x32_bf16 v[14:17], v[156:159], v[218:221], v[14:17]
	v_mfma_f32_16x16x32_bf16 v[10:13], v[164:167], v[218:221], v[10:13]
	s_setprio 0
	s_setprio 1
	v_mfma_f32_16x16x32_bf16 v[54:57], v[168:171], v[190:193], v[54:57]
	v_mfma_f32_16x16x32_bf16 v[50:53], v[176:179], v[190:193], v[50:53]
	v_mfma_f32_16x16x32_bf16 v[38:41], v[168:171], v[198:201], v[38:41]
	v_mfma_f32_16x16x32_bf16 v[34:37], v[176:179], v[198:201], v[34:37]
	v_mfma_f32_16x16x32_bf16 v[22:25], v[168:171], v[206:209], v[22:25]
	v_mfma_f32_16x16x32_bf16 v[18:21], v[176:179], v[206:209], v[18:21]
	v_mfma_f32_16x16x32_bf16 v[6:9], v[168:171], v[214:217], v[6:9]
	v_mfma_f32_16x16x32_bf16 v[2:5], v[176:179], v[214:217], v[2:5]
	v_mfma_f32_16x16x32_bf16 v[54:57], v[172:175], v[194:197], v[54:57]
	v_mfma_f32_16x16x32_bf16 v[50:53], v[186:189], v[194:197], v[50:53]
	v_mfma_f32_16x16x32_bf16 v[38:41], v[172:175], v[202:205], v[38:41]
	v_mfma_f32_16x16x32_bf16 v[34:37], v[186:189], v[202:205], v[34:37]
	v_mfma_f32_16x16x32_bf16 v[22:25], v[172:175], v[210:213], v[22:25]
	v_mfma_f32_16x16x32_bf16 v[18:21], v[186:189], v[210:213], v[18:21]
	v_mfma_f32_16x16x32_bf16 v[6:9], v[172:175], v[218:221], v[6:9]
	v_mfma_f32_16x16x32_bf16 v[2:5], v[186:189], v[218:221], v[2:5]
	s_setprio 0
	s_barrier
	s_add_i32 s47, s47, 2
	s_add_u32 s8, s8, 0x10000
	s_addc_u32 s9, s9, 0
	s_add_u32 s45, s45, 0x10000
	s_addc_u32 s46, s46, 0
	s_cmp_gt_u32 s47, 61
	s_cbranch_scc0 .LBB0_1482
	s_and_b64 vcc, exec, s[20:21]
	s_cbranch_vccz .LBB0_1485
	s_barrier

; #define PG8_STAGE(bufoff, gbase, voff) do { _Pragma("unroll") for (int _i = 0; _i < 2; ++_i) \
;         __builtin_amdgcn_global_load_lds((const unsigned*)((const char*)(gbase) + (voff)[_i]), (LAS unsigned*)(lds + (bufoff) + ldsw + _i * 8192), 16, 0, 0); } while (0)
; #define PG8_LDA(dst, b, h) do { _Pragma("unroll") for (int m = 0; m < 4; ++m) _Pragma("unroll") for (int k = 0; k < 2; ++k) dst[m][k] = *(const LAS bf16x8*)(lds + PG8_SA(b, h) + aoff + m * 2048 + k * 1024); } while (0)
; #define PG8_LDB(dst, b, h) do { _Pragma("unroll") for (int n = 0; n < 2; ++n) _Pragma("unroll") for (int k = 0; k < 2; ++k) dst[n][k] = *(const LAS bf16x8*)(lds + PG8_SB(b, h) + boff + n * 2048 + k * 1024); } while (0)
; #define PG8_WAIT_V(n) asm volatile("s_waitcnt vmcnt(" #n ")" ::: "memory")
; #define PG8_WAIT_L(n) asm volatile("s_waitcnt lgkmcnt(" #n ")" ::: "memory")
; #define PG8_BAR __builtin_amdgcn_s_barrier()
; #define PG8_SCHED __builtin_amdgcn_sched_barrier(0)
; template <class Epi, class Sched, bool I8 = false>
; __device__ __forceinline__ void gemm_phase(LAS unsigned char* lds, const Gemm g, const Sched& S, const Epi& E) {
;     ...
;         for (int t = 0; t < nt; t += 2) {
;             const bool last = (t == nt - 2);
;             const char* a1 = cA + (size_t)(t + 1) * kstep;
;             const char* a2 = last ? nA : cA + (size_t)(t + 2) * kstep; const char* b2 = last ? nB : cB + (size_t)(t + 2) * kstep;
;             const char* a3 = a2 + kstep; const char* b3 = b2 + kstep;
;             PG8_LDB(B0, 0, 0); PG8_LDB(B1, 0, 1); PG8_SCHED; PG8_LDA(At, 0, 0); PG8_STAGE(PG8_SA(1, 1), a1 + hstepA, voffA);
;             PG8_WAIT_V(8); PG8_WAIT_L(0); PG8_BAR; PG8_MMA(0, 0, At, B0); PG8_MMA(0, 1, At, B1); PG8_BAR; PG8_SCHED;
;             PG8_LDA(At, 0, 1); PG8_STAGE(PG8_SB(0, 0), b2, voffB); PG8_STAGE(PG8_SB(0, 1), b2 + hstepB, voffB); PG8_STAGE(PG8_SA(0, 0), a2, voffA);
;             PG8_WAIT_V(8); PG8_WAIT_L(0); PG8_BAR; PG8_MMA(1, 0, At, B0); PG8_MMA(1, 1, At, B1); PG8_BAR; PG8_SCHED;
.LBB0_2685:
	ds_read_b128 v[130:133], v166
	ds_read_b128 v[134:137], v166 offset:1024
	ds_read_b128 v[158:161], v166 offset:2048
	ds_read_b128 v[170:173], v166 offset:3072
	ds_read_b128 v[174:177], v167
	ds_read_b128 v[178:181], v167 offset:1024
	ds_read_b128 v[182:185], v167 offset:2048
	ds_read_b128 v[186:189], v167 offset:3072
	s_add_u32 s12, s10, 0x4000
	s_addc_u32 s13, s11, 0
	s_cmp_eq_u32 s45, 4
	s_cselect_b32 s16, s40, s12
	s_cselect_b32 s17, s39, s13
	s_cselect_b32 s14, s42, s43
	s_cselect_b32 s15, s41, s44
	s_add_u32 s12, s16, 0x8000
	s_addc_u32 s13, s17, 0
	s_sub_u32 s98, s10, 0x4000
	s_subb_u32 s99, s11, 0
	s_mov_b32 m0, s33
	s_nop 0
	global_load_lds_dwordx4 v144, s[98:99]
	s_mov_b32 m0, s34
	s_nop 0
	global_load_lds_dwordx4 v140, s[98:99]
	s_add_i32 m0, s26, 0xc000
	ds_read_b128 v[190:193], v168
	ds_read_b128 v[194:197], v168 offset:1024
	ds_read_b128 v[198:201], v168 offset:2048
	ds_read_b128 v[202:205], v168 offset:3072
	ds_read_b128 v[206:209], v168 offset:4096
	ds_read_b128 v[210:213], v168 offset:5120
	ds_read_b128 v[214:217], v168 offset:6144
	ds_read_b128 v[218:221], v168 offset:7168
	global_load_lds_dwordx4 v150, s[10:11]
	s_add_i32 m0, s26, 0xe000
	s_nop 0
	global_load_lds_dwordx4 v152, s[10:11]
	s_waitcnt vmcnt(8)
	s_waitcnt lgkmcnt(0)
	s_barrier
	s_setprio 1
	s_waitcnt lgkmcnt(0)
	v_mfma_f32_16x16x32_bf16 v[126:129], v[130:133], v[190:193], v[126:129]
	v_mfma_f32_16x16x32_bf16 v[122:125], v[158:161], v[190:193], v[122:125]
	v_mfma_f32_16x16x32_bf16 v[118:121], v[130:133], v[198:201], v[118:121]
	v_mfma_f32_16x16x32_bf16 v[114:117], v[158:161], v[198:201], v[114:117]
	v_mfma_f32_16x16x32_bf16 v[110:113], v[130:133], v[206:209], v[110:113]
	v_mfma_f32_16x16x32_bf16 v[106:109], v[158:161], v[206:209], v[106:109]
	v_mfma_f32_16x16x32_bf16 v[102:105], v[130:133], v[214:217], v[102:105]
	v_mfma_f32_16x16x32_bf16 v[98:101], v[158:161], v[214:217], v[98:101]
	v_mfma_f32_16x16x32_bf16 v[126:129], v[134:137], v[194:197], v[126:129]
	v_mfma_f32_16x16x32_bf16 v[122:125], v[170:173], v[194:197], v[122:125]
	v_mfma_f32_16x16x32_bf16 v[118:121], v[134:137], v[202:205], v[118:121]
	v_mfma_f32_16x16x32_bf16 v[114:117], v[170:173], v[202:205], v[114:117]
	v_mfma_f32_16x16x32_bf16 v[110:113], v[134:137], v[210:213], v[110:113]
	v_mfma_f32_16x16x32_bf16 v[106:109], v[170:173], v[210:213], v[106:109]
	v_mfma_f32_16x16x32_bf16 v[102:105], v[134:137], v[218:221], v[102:105]
	v_mfma_f32_16x16x32_bf16 v[98:101], v[170:173], v[218:221], v[98:101]
	s_setprio 0
	s_setprio 1
	v_mfma_f32_16x16x32_bf16 v[62:65], v[174:177], v[190:193], v[62:65]
	v_mfma_f32_16x16x32_bf16 v[58:61], v[182:185], v[190:193], v[58:61]
	v_mfma_f32_16x16x32_bf16 v[54:57], v[174:177], v[198:201], v[54:57]
	v_mfma_f32_16x16x32_bf16 v[50:53], v[182:185], v[198:201], v[50:53]
	v_mfma_f32_16x16x32_bf16 v[46:49], v[174:177], v[206:209], v[46:49]
	v_mfma_f32_16x16x32_bf16 v[42:45], v[182:185], v[206:209], v[42:45]
	v_mfma_f32_16x16x32_bf16 v[38:41], v[174:177], v[214:217], v[38:41]
	v_mfma_f32_16x16x32_bf16 v[34:37], v[182:185], v[214:217], v[34:37]
	v_mfma_f32_16x16x32_bf16 v[62:65], v[178:181], v[194:197], v[62:65]
	v_mfma_f32_16x16x32_bf16 v[58:61], v[186:189], v[194:197], v[58:61]
	v_mfma_f32_16x16x32_bf16 v[54:57], v[178:181], v[202:205], v[54:57]
	v_mfma_f32_16x16x32_bf16 v[50:53], v[186:189], v[202:205], v[50:53]
	v_mfma_f32_16x16x32_bf16 v[46:49], v[178:181], v[210:213], v[46:49]
	v_mfma_f32_16x16x32_bf16 v[42:45], v[186:189], v[210:213], v[42:45]
	v_mfma_f32_16x16x32_bf16 v[38:41], v[178:181], v[218:221], v[38:41]
	v_mfma_f32_16x16x32_bf16 v[34:37], v[186:189], v[218:221], v[34:37]
	s_setprio 0
	s_barrier
	s_add_i32 s46, s62, s22
	s_mov_b32 m0, s46
	ds_read_b128 v[190:193], v168 offset:16384
	ds_read_b128 v[194:197], v168 offset:17408
	ds_read_b128 v[198:201], v168 offset:18432
	ds_read_b128 v[202:205], v168 offset:19456
	ds_read_b128 v[206:209], v168 offset:20480
	ds_read_b128 v[210:213], v168 offset:21504
	ds_read_b128 v[214:217], v168 offset:22528
	ds_read_b128 v[218:221], v168 offset:23552
	global_load_lds_dwordx4 v142, s[14:15]
	s_add_i32 m0, s46, 0x2000
	s_add_u32 s46, s14, 0x4000
	s_addc_u32 s47, s15, 0
	s_add_i32 s48, s35, s22
	global_load_lds_dwordx4 v138, s[14:15]
	s_mov_b32 m0, s48
	s_nop 0
	global_load_lds_dwordx4 v142, s[46:47]
	s_add_i32 m0, s48, 0x2000
	s_nop 0
	global_load_lds_dwordx4 v138, s[46:47]
	s_waitcnt vmcnt(6)
	s_waitcnt lgkmcnt(0)
	s_barrier
	s_setprio 1
	s_waitcnt lgkmcnt(0)
	v_mfma_f32_16x16x32_bf16 v[94:97], v[130:133], v[190:193], v[94:97]
	v_mfma_f32_16x16x32_bf16 v[90:93], v[158:161], v[190:193], v[90:93]
	v_mfma_f32_16x16x32_bf16 v[86:89], v[130:133], v[198:201], v[86:89]
	v_mfma_f32_16x16x32_bf16 v[82:85], v[158:161], v[198:201], v[82:85]
	v_mfma_f32_16x16x32_bf16 v[78:81], v[130:133], v[206:209], v[78:81]
	v_mfma_f32_16x16x32_bf16 v[74:77], v[158:161], v[206:209], v[74:77]
	v_mfma_f32_16x16x32_bf16 v[70:73], v[130:133], v[214:217], v[70:73]
	v_mfma_f32_16x16x32_bf16 v[66:69], v[158:161], v[214:217], v[66:69]
	v_mfma_f32_16x16x32_bf16 v[94:97], v[134:137], v[194:197], v[94:97]
	v_mfma_f32_16x16x32_bf16 v[90:93], v[170:173], v[194:197], v[90:93]
	v_mfma_f32_16x16x32_bf16 v[86:89], v[134:137], v[202:205], v[86:89]
	v_mfma_f32_16x16x32_bf16 v[82:85], v[170:173], v[202:205], v[82:85]
	v_mfma_f32_16x16x32_bf16 v[78:81], v[134:137], v[210:213], v[78:81]
	v_mfma_f32_16x16x32_bf16 v[74:77], v[170:173], v[210:213], v[74:77]
	v_mfma_f32_16x16x32_bf16 v[70:73], v[134:137], v[218:221], v[70:73]
	v_mfma_f32_16x16x32_bf16 v[66:69], v[170:173], v[218:221], v[66:69]
	s_setprio 0
	s_setprio 1
	v_mfma_f32_16x16x32_bf16 v[30:33], v[174:177], v[190:193], v[30:33]
	v_mfma_f32_16x16x32_bf16 v[26:29], v[182:185], v[190:193], v[26:29]
	v_mfma_f32_16x16x32_bf16 v[22:25], v[174:177], v[198:201], v[22:25]
	v_mfma_f32_16x16x32_bf16 v[18:21], v[182:185], v[198:201], v[18:21]
	v_mfma_f32_16x16x32_bf16 v[14:17], v[174:177], v[206:209], v[14:17]
	v_mfma_f32_16x16x32_bf16 v[10:13], v[182:185], v[206:209], v[10:13]
	v_mfma_f32_16x16x32_bf16 v[6:9], v[174:177], v[214:217], v[6:9]
	v_mfma_f32_16x16x32_bf16 v[2:5], v[182:185], v[214:217], v[2:5]
	v_mfma_f32_16x16x32_bf16 v[30:33], v[178:181], v[194:197], v[30:33]
	v_mfma_f32_16x16x32_bf16 v[26:29], v[186:189], v[194:197], v[26:29]
	v_mfma_f32_16x16x32_bf16 v[22:25], v[178:181], v[202:205], v[22:25]
	v_mfma_f32_16x16x32_bf16 v[18:21], v[186:189], v[202:205], v[18:21]
	v_mfma_f32_16x16x32_bf16 v[14:17], v[178:181], v[210:213], v[14:17]
	v_mfma_f32_16x16x32_bf16 v[10:13], v[186:189], v[210:213], v[10:13]
	v_mfma_f32_16x16x32_bf16 v[6:9], v[178:181], v[218:221], v[6:9]
	v_mfma_f32_16x16x32_bf16 v[2:5], v[186:189], v[218:221], v[2:5]
	s_setprio 0
	s_barrier
; #define PG8_STAGE(bufoff, gbase, voff) do { _Pragma("unroll") for (int _i = 0; _i < 2; ++_i) \
;         __builtin_amdgcn_global_load_lds((const unsigned*)((const char*)(gbase) + (voff)[_i]), (LAS unsigned*)(lds + (bufoff) + ldsw + _i * 8192), 16, 0, 0); } while (0)
; #define PG8_LDA(dst, b, h) do { _Pragma("unroll") for (int m = 0; m < 4; ++m) _Pragma("unroll") for (int k = 0; k < 2; ++k) dst[m][k] = *(const LAS bf16x8*)(lds + PG8_SA(b, h) + aoff + m * 2048 + k * 1024); } while (0)
; #define PG8_LDB(dst, b, h) do { _Pragma("unroll") for (int n = 0; n < 2; ++n) _Pragma("unroll") for (int k = 0; k < 2; ++k) dst[n][k] = *(const LAS bf16x8*)(lds + PG8_SB(b, h) + boff + n * 2048 + k * 1024); } while (0)
; #define PG8_WAIT_V(n) asm volatile("s_waitcnt vmcnt(" #n ")" ::: "memory")
; #define PG8_WAIT_L(n) asm volatile("s_waitcnt lgkmcnt(" #n ")" ::: "memory")
; #define PG8_BAR __builtin_amdgcn_s_barrier()
; #define PG8_SCHED __builtin_amdgcn_sched_barrier(0)
; template <class Epi, class Sched, bool I8 = false>
; __device__ __forceinline__ void gemm_phase(LAS unsigned char* lds, const Gemm g, const Sched& S, const Epi& E) {
;     ...
;             PG8_LDB(B0, 1, 0); PG8_LDB(B1, 1, 1); PG8_SCHED; PG8_LDA(At, 1, 0); PG8_STAGE(PG8_SA(0, 1), a2 + hstepA, voffA);
;             PG8_WAIT_V(8); PG8_WAIT_L(0); PG8_BAR; PG8_MMA(0, 0, At, B0); PG8_MMA(0, 1, At, B1); PG8_BAR; PG8_SCHED;
;             PG8_LDA(At, 1, 1); PG8_STAGE(PG8_SB(1, 0), b3, voffB); PG8_STAGE(PG8_SB(1, 1), b3 + hstepB, voffB); PG8_STAGE(PG8_SA(1, 0), a3, voffA);
;             PG8_WAIT_V(8); PG8_WAIT_L(0); PG8_BAR; PG8_MMA(1, 0, At, B0); PG8_MMA(1, 1, At, B1); PG8_BAR; PG8_SCHED;
;         }
	s_add_i32 s46, 0, 0x18000
	v_add_u32_e32 v155, s46, v165
	s_add_i32 s47, 0, 0x1c000
	ds_read_b128 v[130:133], v155
	ds_read_b128 v[134:137], v155 offset:1024
	ds_read_b128 v[158:161], v155 offset:2048
	ds_read_b128 v[170:173], v155 offset:3072
	v_add_u32_e32 v155, s47, v165
	ds_read_b128 v[174:177], v155
	ds_read_b128 v[178:181], v155 offset:1024
	ds_read_b128 v[182:185], v155 offset:2048
	ds_read_b128 v[186:189], v155 offset:3072
	s_mov_b32 m0, s26
	s_nop 0
	global_load_lds_dwordx4 v144, s[16:17]
	s_mov_b32 m0, s27
	s_nop 0
	global_load_lds_dwordx4 v140, s[16:17]
	s_add_u32 s16, s16, 0x4000
	s_addc_u32 s17, s17, 0
	s_mov_b32 m0, s28
	ds_read_b128 v[190:193], v168 offset:32768
	ds_read_b128 v[194:197], v168 offset:33792
	ds_read_b128 v[198:201], v168 offset:34816
	ds_read_b128 v[202:205], v168 offset:35840
	ds_read_b128 v[206:209], v168 offset:36864
	ds_read_b128 v[210:213], v168 offset:37888
	ds_read_b128 v[214:217], v168 offset:38912
	ds_read_b128 v[218:221], v168 offset:39936
	global_load_lds_dwordx4 v144, s[16:17]
	s_mov_b32 m0, s29
	s_nop 0
	global_load_lds_dwordx4 v140, s[16:17]
	s_waitcnt vmcnt(8)
	s_waitcnt lgkmcnt(0)
	s_barrier
	s_setprio 1
	s_waitcnt lgkmcnt(0)
	v_mfma_f32_16x16x32_bf16 v[126:129], v[130:133], v[190:193], v[126:129]
	v_mfma_f32_16x16x32_bf16 v[122:125], v[158:161], v[190:193], v[122:125]
	v_mfma_f32_16x16x32_bf16 v[118:121], v[130:133], v[198:201], v[118:121]
	v_mfma_f32_16x16x32_bf16 v[114:117], v[158:161], v[198:201], v[114:117]
	v_mfma_f32_16x16x32_bf16 v[110:113], v[130:133], v[206:209], v[110:113]
	v_mfma_f32_16x16x32_bf16 v[106:109], v[158:161], v[206:209], v[106:109]
	v_mfma_f32_16x16x32_bf16 v[102:105], v[130:133], v[214:217], v[102:105]
	v_mfma_f32_16x16x32_bf16 v[98:101], v[158:161], v[214:217], v[98:101]
	v_mfma_f32_16x16x32_bf16 v[126:129], v[134:137], v[194:197], v[126:129]
	v_mfma_f32_16x16x32_bf16 v[122:125], v[170:173], v[194:197], v[122:125]
	v_mfma_f32_16x16x32_bf16 v[118:121], v[134:137], v[202:205], v[118:121]
	v_mfma_f32_16x16x32_bf16 v[114:117], v[170:173], v[202:205], v[114:117]
	v_mfma_f32_16x16x32_bf16 v[110:113], v[134:137], v[210:213], v[110:113]
	v_mfma_f32_16x16x32_bf16 v[106:109], v[170:173], v[210:213], v[106:109]
	v_mfma_f32_16x16x32_bf16 v[102:105], v[134:137], v[218:221], v[102:105]
	v_mfma_f32_16x16x32_bf16 v[98:101], v[170:173], v[218:221], v[98:101]
	s_setprio 0
	s_setprio 1
	v_mfma_f32_16x16x32_bf16 v[62:65], v[174:177], v[190:193], v[62:65]
	v_mfma_f32_16x16x32_bf16 v[58:61], v[182:185], v[190:193], v[58:61]
	v_mfma_f32_16x16x32_bf16 v[54:57], v[174:177], v[198:201], v[54:57]
	v_mfma_f32_16x16x32_bf16 v[50:53], v[182:185], v[198:201], v[50:53]
	v_mfma_f32_16x16x32_bf16 v[46:49], v[174:177], v[206:209], v[46:49]
	v_mfma_f32_16x16x32_bf16 v[42:45], v[182:185], v[206:209], v[42:45]
	v_mfma_f32_16x16x32_bf16 v[38:41], v[174:177], v[214:217], v[38:41]
	v_mfma_f32_16x16x32_bf16 v[34:37], v[182:185], v[214:217], v[34:37]
	v_mfma_f32_16x16x32_bf16 v[62:65], v[178:181], v[194:197], v[62:65]
	v_mfma_f32_16x16x32_bf16 v[58:61], v[186:189], v[194:197], v[58:61]
	v_mfma_f32_16x16x32_bf16 v[54:57], v[178:181], v[202:205], v[54:57]
	v_mfma_f32_16x16x32_bf16 v[50:53], v[186:189], v[202:205], v[50:53]
	v_mfma_f32_16x16x32_bf16 v[46:49], v[178:181], v[210:213], v[46:49]
	v_mfma_f32_16x16x32_bf16 v[42:45], v[186:189], v[210:213], v[42:45]
	v_mfma_f32_16x16x32_bf16 v[38:41], v[178:181], v[218:221], v[38:41]
	v_mfma_f32_16x16x32_bf16 v[34:37], v[186:189], v[218:221], v[34:37]
	s_setprio 0
	s_barrier
	s_add_u32 s16, s14, 0x8000
	s_addc_u32 s17, s15, 0
	s_add_i32 s46, s46, s22
	s_mov_b32 m0, s46
	ds_read_b128 v[190:193], v168 offset:49152
	ds_read_b128 v[194:197], v168 offset:50176
	ds_read_b128 v[198:201], v168 offset:51200
	ds_read_b128 v[202:205], v168 offset:52224
	ds_read_b128 v[206:209], v168 offset:53248
	ds_read_b128 v[210:213], v168 offset:54272
	ds_read_b128 v[214:217], v168 offset:55296
	ds_read_b128 v[218:221], v168 offset:56320
	global_load_lds_dwordx4 v142, s[16:17]
	s_add_i32 m0, s46, 0x2000
	s_add_u32 s14, s14, 0xc000
	v_lshl_add_u64 v[162:163], s[16:17], 0, v[138:139]
	s_addc_u32 s15, s15, 0
	s_add_i32 s16, s47, s22
	global_load_lds_dwordx4 v[162:163], off
	s_mov_b32 m0, s16
	s_nop 0
	global_load_lds_dwordx4 v142, s[14:15]
	s_add_i32 m0, s16, 0x2000
	s_nop 0
	global_load_lds_dwordx4 v138, s[14:15]
	s_waitcnt vmcnt(6)
	s_waitcnt lgkmcnt(0)
	s_barrier
	s_setprio 1
	s_waitcnt lgkmcnt(0)
	v_mfma_f32_16x16x32_bf16 v[94:97], v[130:133], v[190:193], v[94:97]
	v_mfma_f32_16x16x32_bf16 v[90:93], v[158:161], v[190:193], v[90:93]
	v_mfma_f32_16x16x32_bf16 v[86:89], v[130:133], v[198:201], v[86:89]
	v_mfma_f32_16x16x32_bf16 v[82:85], v[158:161], v[198:201], v[82:85]
	v_mfma_f32_16x16x32_bf16 v[78:81], v[130:133], v[206:209], v[78:81]
	v_mfma_f32_16x16x32_bf16 v[74:77], v[158:161], v[206:209], v[74:77]
	v_mfma_f32_16x16x32_bf16 v[70:73], v[130:133], v[214:217], v[70:73]
	v_mfma_f32_16x16x32_bf16 v[66:69], v[158:161], v[214:217], v[66:69]
	v_mfma_f32_16x16x32_bf16 v[94:97], v[134:137], v[194:197], v[94:97]
	v_mfma_f32_16x16x32_bf16 v[90:93], v[170:173], v[194:197], v[90:93]
	v_mfma_f32_16x16x32_bf16 v[86:89], v[134:137], v[202:205], v[86:89]
	v_mfma_f32_16x16x32_bf16 v[82:85], v[170:173], v[202:205], v[82:85]
	v_mfma_f32_16x16x32_bf16 v[78:81], v[134:137], v[210:213], v[78:81]
	v_mfma_f32_16x16x32_bf16 v[74:77], v[170:173], v[210:213], v[74:77]
	v_mfma_f32_16x16x32_bf16 v[70:73], v[134:137], v[218:221], v[70:73]
	v_mfma_f32_16x16x32_bf16 v[66:69], v[170:173], v[218:221], v[66:69]
	s_setprio 0
	s_setprio 1
	v_mfma_f32_16x16x32_bf16 v[30:33], v[174:177], v[190:193], v[30:33]
	v_mfma_f32_16x16x32_bf16 v[26:29], v[182:185], v[190:193], v[26:29]
	v_mfma_f32_16x16x32_bf16 v[22:25], v[174:177], v[198:201], v[22:25]
	v_mfma_f32_16x16x32_bf16 v[18:21], v[182:185], v[198:201], v[18:21]
	v_mfma_f32_16x16x32_bf16 v[14:17], v[174:177], v[206:209], v[14:17]
	v_mfma_f32_16x16x32_bf16 v[10:13], v[182:185], v[206:209], v[10:13]
	v_mfma_f32_16x16x32_bf16 v[6:9], v[174:177], v[214:217], v[6:9]
	v_mfma_f32_16x16x32_bf16 v[2:5], v[182:185], v[214:217], v[2:5]
	v_mfma_f32_16x16x32_bf16 v[30:33], v[178:181], v[194:197], v[30:33]
	v_mfma_f32_16x16x32_bf16 v[26:29], v[186:189], v[194:197], v[26:29]
	v_mfma_f32_16x16x32_bf16 v[22:25], v[178:181], v[202:205], v[22:25]
	v_mfma_f32_16x16x32_bf16 v[18:21], v[186:189], v[202:205], v[18:21]
	v_mfma_f32_16x16x32_bf16 v[14:17], v[178:181], v[210:213], v[14:17]
	v_mfma_f32_16x16x32_bf16 v[10:13], v[186:189], v[210:213], v[10:13]
	v_mfma_f32_16x16x32_bf16 v[6:9], v[178:181], v[218:221], v[6:9]
	v_mfma_f32_16x16x32_bf16 v[2:5], v[186:189], v[218:221], v[2:5]
	s_setprio 0
	s_barrier
	s_add_i32 s45, s45, 2
	s_add_u32 s10, s10, 0x10000
	s_addc_u32 s11, s11, 0
	s_add_u32 s43, s43, 0x10000
	s_addc_u32 s44, s44, 0
	s_cmp_gt_u32 s45, 5
	s_cbranch_scc0 .LBB0_2685
	s_and_b64 vcc, exec, s[6:7]
	s_cbranch_vccz .LBB0_2688
	s_barrier

; #define PG8_STAGE(bufoff, gbase, voff) do { _Pragma("unroll") for (int _i = 0; _i < 2; ++_i) \
;         __builtin_amdgcn_global_load_lds((const unsigned*)((const char*)(gbase) + (voff)[_i]), (LAS unsigned*)(lds + (bufoff) + ldsw + _i * 8192), 16, 0, 0); } while (0)
; #define PG8_LDA(dst, b, h) do { _Pragma("unroll") for (int m = 0; m < 4; ++m) _Pragma("unroll") for (int k = 0; k < 2; ++k) dst[m][k] = *(const LAS bf16x8*)(lds + PG8_SA(b, h) + aoff + m * 2048 + k * 1024); } while (0)
; #define PG8_LDB(dst, b, h) do { _Pragma("unroll") for (int n = 0; n < 2; ++n) _Pragma("unroll") for (int k = 0; k < 2; ++k) dst[n][k] = *(const LAS bf16x8*)(lds + PG8_SB(b, h) + boff + n * 2048 + k * 1024); } while (0)
; #define PG8_WAIT_V(n) asm volatile("s_waitcnt vmcnt(" #n ")" ::: "memory")
; #define PG8_WAIT_L(n) asm volatile("s_waitcnt lgkmcnt(" #n ")" ::: "memory")
; #define PG8_BAR __builtin_amdgcn_s_barrier()
; #define PG8_SCHED __builtin_amdgcn_sched_barrier(0)
; template <class Epi, class Sched, bool I8 = false>
; __device__ __forceinline__ void gemm_phase(LAS unsigned char* lds, const Gemm g, const Sched& S, const Epi& E) {
;     ...
;         for (int t = 0; t < nt; t += 2) {
;             const bool last = (t == nt - 2);
;             const char* a1 = cA + (size_t)(t + 1) * kstep;
;             const char* a2 = last ? nA : cA + (size_t)(t + 2) * kstep; const char* b2 = last ? nB : cB + (size_t)(t + 2) * kstep;
;             const char* a3 = a2 + kstep; const char* b3 = b2 + kstep;
;             PG8_LDB(B0, 0, 0); PG8_LDB(B1, 0, 1); PG8_SCHED; PG8_LDA(At, 0, 0); PG8_STAGE(PG8_SA(1, 1), a1 + hstepA, voffA);
;             PG8_WAIT_V(8); PG8_WAIT_L(0); PG8_BAR; PG8_MMA(0, 0, At, B0); PG8_MMA(0, 1, At, B1); PG8_BAR; PG8_SCHED;
;             PG8_LDA(At, 0, 1); PG8_STAGE(PG8_SB(0, 0), b2, voffB); PG8_STAGE(PG8_SB(0, 1), b2 + hstepB, voffB); PG8_STAGE(PG8_SA(0, 0), a2, voffA);
;             PG8_WAIT_V(8); PG8_WAIT_L(0); PG8_BAR; PG8_MMA(1, 0, At, B0); PG8_MMA(1, 1, At, B1); PG8_BAR; PG8_SCHED;
.LBB0_3744:
	ds_read_b128 v[130:133], v231
	ds_read_b128 v[134:137], v231 offset:1024
	ds_read_b128 v[138:141], v231 offset:2048
	ds_read_b128 v[142:145], v231 offset:3072
	ds_read_b128 v[146:149], v232
	ds_read_b128 v[150:153], v232 offset:1024
	ds_read_b128 v[154:157], v232 offset:2048
	ds_read_b128 v[158:161], v232 offset:3072
	s_add_u32 s34, s30, 0x4000
	s_addc_u32 s35, s31, 0
	s_cmp_eq_u32 s59, 60
	s_cselect_b32 s38, s23, s34
	s_cselect_b32 s39, s5, s35
	s_cselect_b32 s36, s29, s57
	s_cselect_b32 s37, s21, s58
	s_add_u32 s34, s38, 0x8000
	s_addc_u32 s35, s39, 0
	s_sub_u32 s98, s30, 0x4000
	s_subb_u32 s99, s31, 0
	s_mov_b32 m0, s51
	s_nop 0
	global_load_lds_dwordx4 v194, s[98:99]
	s_mov_b32 m0, s52
	s_nop 0
	global_load_lds_dwordx4 v198, s[98:99]
	s_add_i32 m0, s44, 0xc000
	ds_read_b128 v[162:165], v233
	ds_read_b128 v[166:169], v233 offset:1024
	ds_read_b128 v[170:173], v233 offset:2048
	ds_read_b128 v[174:177], v233 offset:3072
	ds_read_b128 v[178:181], v233 offset:4096
	ds_read_b128 v[182:185], v233 offset:5120
	ds_read_b128 v[186:189], v233 offset:6144
	ds_read_b128 v[190:193], v233 offset:7168
	global_load_lds_dwordx4 v204, s[30:31]
	s_add_i32 m0, s44, 0xe000
	s_nop 0
	global_load_lds_dwordx4 v206, s[30:31]
	s_waitcnt vmcnt(8)
	s_waitcnt lgkmcnt(0)
	s_barrier
	s_setprio 1
	s_waitcnt lgkmcnt(0)
	v_mfma_f32_16x16x32_bf16 v[126:129], v[130:133], v[162:165], v[126:129]
	v_mfma_f32_16x16x32_bf16 v[122:125], v[138:141], v[162:165], v[122:125]
	v_mfma_f32_16x16x32_bf16 v[118:121], v[130:133], v[170:173], v[118:121]
	v_mfma_f32_16x16x32_bf16 v[110:113], v[138:141], v[170:173], v[110:113]
	v_mfma_f32_16x16x32_bf16 v[102:105], v[130:133], v[178:181], v[102:105]
	v_mfma_f32_16x16x32_bf16 v[94:97], v[138:141], v[178:181], v[94:97]
	v_mfma_f32_16x16x32_bf16 v[86:89], v[130:133], v[186:189], v[86:89]
	v_mfma_f32_16x16x32_bf16 v[78:81], v[138:141], v[186:189], v[78:81]
	v_mfma_f32_16x16x32_bf16 v[126:129], v[134:137], v[166:169], v[126:129]
	v_mfma_f32_16x16x32_bf16 v[122:125], v[142:145], v[166:169], v[122:125]
	v_mfma_f32_16x16x32_bf16 v[118:121], v[134:137], v[174:177], v[118:121]
	v_mfma_f32_16x16x32_bf16 v[110:113], v[142:145], v[174:177], v[110:113]
	v_mfma_f32_16x16x32_bf16 v[102:105], v[134:137], v[182:185], v[102:105]
	v_mfma_f32_16x16x32_bf16 v[94:97], v[142:145], v[182:185], v[94:97]
	v_mfma_f32_16x16x32_bf16 v[86:89], v[134:137], v[190:193], v[86:89]
	v_mfma_f32_16x16x32_bf16 v[78:81], v[142:145], v[190:193], v[78:81]
	s_setprio 0
	s_setprio 1
	v_mfma_f32_16x16x32_bf16 v[114:117], v[146:149], v[162:165], v[114:117]
	v_mfma_f32_16x16x32_bf16 v[106:109], v[154:157], v[162:165], v[106:109]
	v_mfma_f32_16x16x32_bf16 v[98:101], v[146:149], v[170:173], v[98:101]
	v_mfma_f32_16x16x32_bf16 v[90:93], v[154:157], v[170:173], v[90:93]
	v_mfma_f32_16x16x32_bf16 v[82:85], v[146:149], v[178:181], v[82:85]
	v_mfma_f32_16x16x32_bf16 v[74:77], v[154:157], v[178:181], v[74:77]
	v_mfma_f32_16x16x32_bf16 v[70:73], v[146:149], v[186:189], v[70:73]
	v_mfma_f32_16x16x32_bf16 v[66:69], v[154:157], v[186:189], v[66:69]
	v_mfma_f32_16x16x32_bf16 v[114:117], v[150:153], v[166:169], v[114:117]
	v_mfma_f32_16x16x32_bf16 v[106:109], v[158:161], v[166:169], v[106:109]
	v_mfma_f32_16x16x32_bf16 v[98:101], v[150:153], v[174:177], v[98:101]
	v_mfma_f32_16x16x32_bf16 v[90:93], v[158:161], v[174:177], v[90:93]
	v_mfma_f32_16x16x32_bf16 v[82:85], v[150:153], v[182:185], v[82:85]
	v_mfma_f32_16x16x32_bf16 v[74:77], v[158:161], v[182:185], v[74:77]
	v_mfma_f32_16x16x32_bf16 v[70:73], v[150:153], v[190:193], v[70:73]
	v_mfma_f32_16x16x32_bf16 v[66:69], v[158:161], v[190:193], v[66:69]
	s_setprio 0
	s_barrier
	s_add_i32 s60, s55, s43
	s_mov_b32 m0, s60
	ds_read_b128 v[162:165], v233 offset:16384
	ds_read_b128 v[166:169], v233 offset:17408
	ds_read_b128 v[170:173], v233 offset:18432
	ds_read_b128 v[174:177], v233 offset:19456
	ds_read_b128 v[178:181], v233 offset:20480
	ds_read_b128 v[182:185], v233 offset:21504
	ds_read_b128 v[186:189], v233 offset:22528
	ds_read_b128 v[190:193], v233 offset:23552
	global_load_lds_dwordx4 v196, s[36:37]
	s_add_i32 m0, s60, 0x2000
	s_add_u32 s60, s36, 0x4000
	s_addc_u32 s61, s37, 0
	s_add_i32 s62, s56, s43
	global_load_lds_dwordx4 v200, s[36:37]
	s_mov_b32 m0, s62
	s_nop 0
	global_load_lds_dwordx4 v196, s[60:61]
	s_add_i32 m0, s62, 0x2000
	s_nop 0
	global_load_lds_dwordx4 v200, s[60:61]
	s_waitcnt vmcnt(6)
	s_waitcnt lgkmcnt(0)
	s_barrier
	s_setprio 1
	s_waitcnt lgkmcnt(0)
	v_mfma_f32_16x16x32_bf16 v[62:65], v[130:133], v[162:165], v[62:65]
	v_mfma_f32_16x16x32_bf16 v[58:61], v[138:141], v[162:165], v[58:61]
	v_mfma_f32_16x16x32_bf16 v[54:57], v[130:133], v[170:173], v[54:57]
	v_mfma_f32_16x16x32_bf16 v[46:49], v[138:141], v[170:173], v[46:49]
	v_mfma_f32_16x16x32_bf16 v[38:41], v[130:133], v[178:181], v[38:41]
	v_mfma_f32_16x16x32_bf16 v[30:33], v[138:141], v[178:181], v[30:33]
	v_mfma_f32_16x16x32_bf16 v[22:25], v[130:133], v[186:189], v[22:25]
	v_mfma_f32_16x16x32_bf16 v[14:17], v[138:141], v[186:189], v[14:17]
	v_mfma_f32_16x16x32_bf16 v[62:65], v[134:137], v[166:169], v[62:65]
	v_mfma_f32_16x16x32_bf16 v[58:61], v[142:145], v[166:169], v[58:61]
	v_mfma_f32_16x16x32_bf16 v[54:57], v[134:137], v[174:177], v[54:57]
	v_mfma_f32_16x16x32_bf16 v[46:49], v[142:145], v[174:177], v[46:49]
	v_mfma_f32_16x16x32_bf16 v[38:41], v[134:137], v[182:185], v[38:41]
	v_mfma_f32_16x16x32_bf16 v[30:33], v[142:145], v[182:185], v[30:33]
	v_mfma_f32_16x16x32_bf16 v[22:25], v[134:137], v[190:193], v[22:25]
	v_mfma_f32_16x16x32_bf16 v[14:17], v[142:145], v[190:193], v[14:17]
	s_setprio 0
	s_setprio 1
	v_mfma_f32_16x16x32_bf16 v[50:53], v[146:149], v[162:165], v[50:53]
	v_mfma_f32_16x16x32_bf16 v[42:45], v[154:157], v[162:165], v[42:45]
	v_mfma_f32_16x16x32_bf16 v[34:37], v[146:149], v[170:173], v[34:37]
	v_mfma_f32_16x16x32_bf16 v[26:29], v[154:157], v[170:173], v[26:29]
	v_mfma_f32_16x16x32_bf16 v[18:21], v[146:149], v[178:181], v[18:21]
	v_mfma_f32_16x16x32_bf16 v[10:13], v[154:157], v[178:181], v[10:13]
	v_mfma_f32_16x16x32_bf16 v[6:9], v[146:149], v[186:189], v[6:9]
	v_mfma_f32_16x16x32_bf16 v[2:5], v[154:157], v[186:189], v[2:5]
	v_mfma_f32_16x16x32_bf16 v[50:53], v[150:153], v[166:169], v[50:53]
	v_mfma_f32_16x16x32_bf16 v[42:45], v[158:161], v[166:169], v[42:45]
	v_mfma_f32_16x16x32_bf16 v[34:37], v[150:153], v[174:177], v[34:37]
	v_mfma_f32_16x16x32_bf16 v[26:29], v[158:161], v[174:177], v[26:29]
	v_mfma_f32_16x16x32_bf16 v[18:21], v[150:153], v[182:185], v[18:21]
	v_mfma_f32_16x16x32_bf16 v[10:13], v[158:161], v[182:185], v[10:13]
	v_mfma_f32_16x16x32_bf16 v[6:9], v[150:153], v[190:193], v[6:9]
	v_mfma_f32_16x16x32_bf16 v[2:5], v[158:161], v[190:193], v[2:5]
	s_setprio 0
	s_barrier
; #define PG8_STAGE(bufoff, gbase, voff) do { _Pragma("unroll") for (int _i = 0; _i < 2; ++_i) \
;         __builtin_amdgcn_global_load_lds((const unsigned*)((const char*)(gbase) + (voff)[_i]), (LAS unsigned*)(lds + (bufoff) + ldsw + _i * 8192), 16, 0, 0); } while (0)
; #define PG8_LDA(dst, b, h) do { _Pragma("unroll") for (int m = 0; m < 4; ++m) _Pragma("unroll") for (int k = 0; k < 2; ++k) dst[m][k] = *(const LAS bf16x8*)(lds + PG8_SA(b, h) + aoff + m * 2048 + k * 1024); } while (0)
; #define PG8_LDB(dst, b, h) do { _Pragma("unroll") for (int n = 0; n < 2; ++n) _Pragma("unroll") for (int k = 0; k < 2; ++k) dst[n][k] = *(const LAS bf16x8*)(lds + PG8_SB(b, h) + boff + n * 2048 + k * 1024); } while (0)
; #define PG8_WAIT_V(n) asm volatile("s_waitcnt vmcnt(" #n ")" ::: "memory")
; #define PG8_WAIT_L(n) asm volatile("s_waitcnt lgkmcnt(" #n ")" ::: "memory")
; #define PG8_BAR __builtin_amdgcn_s_barrier()
; #define PG8_SCHED __builtin_amdgcn_sched_barrier(0)
; template <class Epi, class Sched, bool I8 = false>
; __device__ __forceinline__ void gemm_phase(LAS unsigned char* lds, const Gemm g, const Sched& S, const Epi& E) {
;     ...
;             PG8_LDB(B0, 1, 0); PG8_LDB(B1, 1, 1); PG8_SCHED; PG8_LDA(At, 1, 0); PG8_STAGE(PG8_SA(0, 1), a2 + hstepA, voffA);
;             PG8_WAIT_V(8); PG8_WAIT_L(0); PG8_BAR; PG8_MMA(0, 0, At, B0); PG8_MMA(0, 1, At, B1); PG8_BAR; PG8_SCHED;
;             PG8_LDA(At, 1, 1); PG8_STAGE(PG8_SB(1, 0), b3, voffB); PG8_STAGE(PG8_SB(1, 1), b3 + hstepB, voffB); PG8_STAGE(PG8_SA(1, 0), a3, voffA);
;             PG8_WAIT_V(8); PG8_WAIT_L(0); PG8_BAR; PG8_MMA(1, 0, At, B0); PG8_MMA(1, 1, At, B1); PG8_BAR; PG8_SCHED;
;         }
	s_add_i32 s60, 0, 0x18000
	s_add_i32 s61, 0, 0x1c000
	v_add_u32_e32 v142, s60, v230
	v_add_u32_e32 v158, s61, v230
	ds_read_b128 v[130:133], v142
	ds_read_b128 v[134:137], v142 offset:1024
	ds_read_b128 v[138:141], v142 offset:2048
	ds_read_b128 v[142:145], v142 offset:3072
	ds_read_b128 v[146:149], v158
	ds_read_b128 v[150:153], v158 offset:1024
	ds_read_b128 v[154:157], v158 offset:2048
	ds_read_b128 v[158:161], v158 offset:3072
	s_mov_b32 m0, s44
	s_nop 0
	global_load_lds_dwordx4 v194, s[38:39]
	s_mov_b32 m0, s45
	s_nop 0
	global_load_lds_dwordx4 v198, s[38:39]
	s_add_u32 s38, s38, 0x4000
	s_addc_u32 s39, s39, 0
	s_mov_b32 m0, s46
	ds_read_b128 v[162:165], v233 offset:32768
	ds_read_b128 v[166:169], v233 offset:33792
	ds_read_b128 v[170:173], v233 offset:34816
	ds_read_b128 v[174:177], v233 offset:35840
	ds_read_b128 v[178:181], v233 offset:36864
	ds_read_b128 v[182:185], v233 offset:37888
	ds_read_b128 v[186:189], v233 offset:38912
	ds_read_b128 v[190:193], v233 offset:39936
	global_load_lds_dwordx4 v194, s[38:39]
	s_mov_b32 m0, s47
	s_nop 0
	global_load_lds_dwordx4 v198, s[38:39]
	s_waitcnt vmcnt(8)
	s_waitcnt lgkmcnt(0)
	s_barrier
	s_setprio 1
	s_waitcnt lgkmcnt(0)
	v_mfma_f32_16x16x32_bf16 v[126:129], v[130:133], v[162:165], v[126:129]
	v_mfma_f32_16x16x32_bf16 v[122:125], v[138:141], v[162:165], v[122:125]
	v_mfma_f32_16x16x32_bf16 v[118:121], v[130:133], v[170:173], v[118:121]
	v_mfma_f32_16x16x32_bf16 v[110:113], v[138:141], v[170:173], v[110:113]
	v_mfma_f32_16x16x32_bf16 v[102:105], v[130:133], v[178:181], v[102:105]
	v_mfma_f32_16x16x32_bf16 v[94:97], v[138:141], v[178:181], v[94:97]
	v_mfma_f32_16x16x32_bf16 v[86:89], v[130:133], v[186:189], v[86:89]
	v_mfma_f32_16x16x32_bf16 v[78:81], v[138:141], v[186:189], v[78:81]
	v_mfma_f32_16x16x32_bf16 v[126:129], v[134:137], v[166:169], v[126:129]
	v_mfma_f32_16x16x32_bf16 v[122:125], v[142:145], v[166:169], v[122:125]
	v_mfma_f32_16x16x32_bf16 v[118:121], v[134:137], v[174:177], v[118:121]
	v_mfma_f32_16x16x32_bf16 v[110:113], v[142:145], v[174:177], v[110:113]
	v_mfma_f32_16x16x32_bf16 v[102:105], v[134:137], v[182:185], v[102:105]
	v_mfma_f32_16x16x32_bf16 v[94:97], v[142:145], v[182:185], v[94:97]
	v_mfma_f32_16x16x32_bf16 v[86:89], v[134:137], v[190:193], v[86:89]
	v_mfma_f32_16x16x32_bf16 v[78:81], v[142:145], v[190:193], v[78:81]
	s_setprio 0
	s_setprio 1
	v_mfma_f32_16x16x32_bf16 v[114:117], v[146:149], v[162:165], v[114:117]
	v_mfma_f32_16x16x32_bf16 v[106:109], v[154:157], v[162:165], v[106:109]
	v_mfma_f32_16x16x32_bf16 v[98:101], v[146:149], v[170:173], v[98:101]
	v_mfma_f32_16x16x32_bf16 v[90:93], v[154:157], v[170:173], v[90:93]
	v_mfma_f32_16x16x32_bf16 v[82:85], v[146:149], v[178:181], v[82:85]
	v_mfma_f32_16x16x32_bf16 v[74:77], v[154:157], v[178:181], v[74:77]
	v_mfma_f32_16x16x32_bf16 v[70:73], v[146:149], v[186:189], v[70:73]
	v_mfma_f32_16x16x32_bf16 v[66:69], v[154:157], v[186:189], v[66:69]
	v_mfma_f32_16x16x32_bf16 v[114:117], v[150:153], v[166:169], v[114:117]
	v_mfma_f32_16x16x32_bf16 v[106:109], v[158:161], v[166:169], v[106:109]
	v_mfma_f32_16x16x32_bf16 v[98:101], v[150:153], v[174:177], v[98:101]
	v_mfma_f32_16x16x32_bf16 v[90:93], v[158:161], v[174:177], v[90:93]
	v_mfma_f32_16x16x32_bf16 v[82:85], v[150:153], v[182:185], v[82:85]
	v_mfma_f32_16x16x32_bf16 v[74:77], v[158:161], v[182:185], v[74:77]
	v_mfma_f32_16x16x32_bf16 v[70:73], v[150:153], v[190:193], v[70:73]
	v_mfma_f32_16x16x32_bf16 v[66:69], v[158:161], v[190:193], v[66:69]
	s_setprio 0
	s_barrier
	s_add_u32 s38, s36, 0x8000
	s_addc_u32 s39, s37, 0
	s_add_i32 s60, s60, s43
	s_mov_b32 m0, s60
	ds_read_b128 v[162:165], v233 offset:49152
	ds_read_b128 v[166:169], v233 offset:50176
	ds_read_b128 v[170:173], v233 offset:51200
	ds_read_b128 v[174:177], v233 offset:52224
	ds_read_b128 v[178:181], v233 offset:53248
	ds_read_b128 v[182:185], v233 offset:54272
	ds_read_b128 v[186:189], v233 offset:55296
	ds_read_b128 v[190:193], v233 offset:56320
	global_load_lds_dwordx4 v196, s[38:39]
	s_add_i32 m0, s60, 0x2000
	s_add_u32 s36, s36, 0xc000
	v_lshl_add_u64 v[212:213], s[38:39], 0, v[200:201]
	s_addc_u32 s37, s37, 0
	s_add_i32 s38, s61, s43
	global_load_lds_dwordx4 v[212:213], off
	s_mov_b32 m0, s38
	s_nop 0
	global_load_lds_dwordx4 v196, s[36:37]
	s_add_i32 m0, s38, 0x2000
	s_nop 0
	global_load_lds_dwordx4 v200, s[36:37]
	s_waitcnt vmcnt(6)
	s_waitcnt lgkmcnt(0)
	s_barrier
	s_setprio 1
	s_waitcnt lgkmcnt(0)
	v_mfma_f32_16x16x32_bf16 v[62:65], v[130:133], v[162:165], v[62:65]
	v_mfma_f32_16x16x32_bf16 v[58:61], v[138:141], v[162:165], v[58:61]
	v_mfma_f32_16x16x32_bf16 v[54:57], v[130:133], v[170:173], v[54:57]
	v_mfma_f32_16x16x32_bf16 v[46:49], v[138:141], v[170:173], v[46:49]
	v_mfma_f32_16x16x32_bf16 v[38:41], v[130:133], v[178:181], v[38:41]
	v_mfma_f32_16x16x32_bf16 v[30:33], v[138:141], v[178:181], v[30:33]
	v_mfma_f32_16x16x32_bf16 v[22:25], v[130:133], v[186:189], v[22:25]
	v_mfma_f32_16x16x32_bf16 v[14:17], v[138:141], v[186:189], v[14:17]
	v_mfma_f32_16x16x32_bf16 v[62:65], v[134:137], v[166:169], v[62:65]
	v_mfma_f32_16x16x32_bf16 v[58:61], v[142:145], v[166:169], v[58:61]
	v_mfma_f32_16x16x32_bf16 v[54:57], v[134:137], v[174:177], v[54:57]
	v_mfma_f32_16x16x32_bf16 v[46:49], v[142:145], v[174:177], v[46:49]
	v_mfma_f32_16x16x32_bf16 v[38:41], v[134:137], v[182:185], v[38:41]
	v_mfma_f32_16x16x32_bf16 v[30:33], v[142:145], v[182:185], v[30:33]
	v_mfma_f32_16x16x32_bf16 v[22:25], v[134:137], v[190:193], v[22:25]
	v_mfma_f32_16x16x32_bf16 v[14:17], v[142:145], v[190:193], v[14:17]
	s_setprio 0
	s_setprio 1
	v_mfma_f32_16x16x32_bf16 v[50:53], v[146:149], v[162:165], v[50:53]
	v_mfma_f32_16x16x32_bf16 v[42:45], v[154:157], v[162:165], v[42:45]
	v_mfma_f32_16x16x32_bf16 v[34:37], v[146:149], v[170:173], v[34:37]
	v_mfma_f32_16x16x32_bf16 v[26:29], v[154:157], v[170:173], v[26:29]
	v_mfma_f32_16x16x32_bf16 v[18:21], v[146:149], v[178:181], v[18:21]
	v_mfma_f32_16x16x32_bf16 v[10:13], v[154:157], v[178:181], v[10:13]
	v_mfma_f32_16x16x32_bf16 v[6:9], v[146:149], v[186:189], v[6:9]
	v_mfma_f32_16x16x32_bf16 v[2:5], v[154:157], v[186:189], v[2:5]
	v_mfma_f32_16x16x32_bf16 v[50:53], v[150:153], v[166:169], v[50:53]
	v_mfma_f32_16x16x32_bf16 v[42:45], v[158:161], v[166:169], v[42:45]
	v_mfma_f32_16x16x32_bf16 v[34:37], v[150:153], v[174:177], v[34:37]
	v_mfma_f32_16x16x32_bf16 v[26:29], v[158:161], v[174:177], v[26:29]
	v_mfma_f32_16x16x32_bf16 v[18:21], v[150:153], v[182:185], v[18:21]
	v_mfma_f32_16x16x32_bf16 v[10:13], v[158:161], v[182:185], v[10:13]
	v_mfma_f32_16x16x32_bf16 v[6:9], v[150:153], v[190:193], v[6:9]
	v_mfma_f32_16x16x32_bf16 v[2:5], v[158:161], v[190:193], v[2:5]
	s_setprio 0
	s_barrier
	s_add_i32 s59, s59, 2
	s_add_u32 s30, s30, 0x10000
	s_addc_u32 s31, s31, 0
	s_add_u32 s57, s57, 0x10000
	s_addc_u32 s58, s58, 0
	s_cmp_gt_u32 s59, 61
	s_cbranch_scc0 .LBB0_3744
	s_and_b64 vcc, exec, s[6:7]
	s_cbranch_vccz .LBB0_3747
	s_barrier

; #define PG8_STAGE(bufoff, gbase, voff) do { _Pragma("unroll") for (int _i = 0; _i < 2; ++_i) \
;         __builtin_amdgcn_global_load_lds((const unsigned*)((const char*)(gbase) + (voff)[_i]), (LAS unsigned*)(lds + (bufoff) + ldsw + _i * 8192), 16, 0, 0); } while (0)
; #define PG8_LDA(dst, b, h) do { _Pragma("unroll") for (int m = 0; m < 4; ++m) _Pragma("unroll") for (int k = 0; k < 2; ++k) dst[m][k] = *(const LAS bf16x8*)(lds + PG8_SA(b, h) + aoff + m * 2048 + k * 1024); } while (0)
; #define PG8_LDB(dst, b, h) do { _Pragma("unroll") for (int n = 0; n < 2; ++n) _Pragma("unroll") for (int k = 0; k < 2; ++k) dst[n][k] = *(const LAS bf16x8*)(lds + PG8_SB(b, h) + boff + n * 2048 + k * 1024); } while (0)
; #define PG8_WAIT_V(n) asm volatile("s_waitcnt vmcnt(" #n ")" ::: "memory")
; #define PG8_WAIT_L(n) asm volatile("s_waitcnt lgkmcnt(" #n ")" ::: "memory")
; #define PG8_BAR __builtin_amdgcn_s_barrier()
; #define PG8_SCHED __builtin_amdgcn_sched_barrier(0)
; template <class Epi, class Sched, bool I8 = false>
; __device__ __forceinline__ void gemm_phase(LAS unsigned char* lds, const Gemm g, const Sched& S, const Epi& E) {
;     ...
;         for (int t = 0; t < nt; t += 2) {
;             const bool last = (t == nt - 2);
;             const char* a1 = cA + (size_t)(t + 1) * kstep;
;             const char* a2 = last ? nA : cA + (size_t)(t + 2) * kstep; const char* b2 = last ? nB : cB + (size_t)(t + 2) * kstep;
;             const char* a3 = a2 + kstep; const char* b3 = b2 + kstep;
;             PG8_LDB(B0, 0, 0); PG8_LDB(B1, 0, 1); PG8_SCHED; PG8_LDA(At, 0, 0); PG8_STAGE(PG8_SA(1, 1), a1 + hstepA, voffA);
;             PG8_WAIT_V(8); PG8_WAIT_L(0); PG8_BAR; PG8_MMA(0, 0, At, B0); PG8_MMA(0, 1, At, B1); PG8_BAR; PG8_SCHED;
;             PG8_LDA(At, 0, 1); PG8_STAGE(PG8_SB(0, 0), b2, voffB); PG8_STAGE(PG8_SB(0, 1), b2 + hstepB, voffB); PG8_STAGE(PG8_SA(0, 0), a2, voffA);
;             PG8_WAIT_V(8); PG8_WAIT_L(0); PG8_BAR; PG8_MMA(1, 0, At, B0); PG8_MMA(1, 1, At, B1); PG8_BAR; PG8_SCHED;
.LBB0_4168:
	ds_read_b128 v[66:69], v178
	ds_read_b128 v[70:73], v178 offset:1024
	ds_read_b128 v[74:77], v178 offset:2048
	ds_read_b128 v[78:81], v178 offset:3072
	ds_read_b128 v[146:149], v179
	ds_read_b128 v[150:153], v179 offset:1024
	ds_read_b128 v[172:175], v179 offset:2048
	ds_read_b128 v[182:185], v179 offset:3072
	s_add_u32 s22, s20, 0x4000
	s_addc_u32 s23, s21, 0
	s_cmpk_eq_i32 s51, 0x52
	s_cselect_b32 s26, s0, s22
	s_cselect_b32 s27, s1, s23
	s_cselect_b32 s24, s18, s49
	s_cselect_b32 s25, s19, s50
	s_add_u32 s22, s26, 0x8000
	s_addc_u32 s23, s27, 0
	s_sub_u32 s98, s20, 0x4000
	s_subb_u32 s99, s21, 0
	s_mov_b32 m0, s39
	s_nop 0
	global_load_lds_dwordx4 v154, s[98:99]
	s_mov_b32 m0, s40
	s_nop 0
	global_load_lds_dwordx4 v158, s[98:99]
	s_add_i32 m0, s34, 0xc000
	ds_read_b128 v[186:189], v180
	ds_read_b128 v[190:193], v180 offset:1024
	ds_read_b128 v[194:197], v180 offset:2048
	ds_read_b128 v[198:201], v180 offset:3072
	ds_read_b128 v[202:205], v180 offset:4096
	ds_read_b128 v[206:209], v180 offset:5120
	ds_read_b128 v[210:213], v180 offset:6144
	ds_read_b128 v[214:217], v180 offset:7168
	global_load_lds_dwordx4 v164, s[20:21]
	s_add_i32 m0, s34, 0xe000
	s_nop 0
	global_load_lds_dwordx4 v166, s[20:21]
	s_waitcnt vmcnt(8)
	s_waitcnt lgkmcnt(0)
	s_barrier
	s_setprio 1
	s_waitcnt lgkmcnt(0)
	v_mfma_i32_16x16x64_i8 v[142:145], v[66:69], v[186:189], v[142:145]
	v_mfma_i32_16x16x64_i8 v[138:141], v[74:77], v[186:189], v[138:141]
	v_mfma_i32_16x16x64_i8 v[126:129], v[66:69], v[194:197], v[126:129]
	v_mfma_i32_16x16x64_i8 v[122:125], v[74:77], v[194:197], v[122:125]
	v_mfma_i32_16x16x64_i8 v[110:113], v[66:69], v[202:205], v[110:113]
	v_mfma_i32_16x16x64_i8 v[106:109], v[74:77], v[202:205], v[106:109]
	v_mfma_i32_16x16x64_i8 v[94:97], v[66:69], v[210:213], v[94:97]
	v_mfma_i32_16x16x64_i8 v[90:93], v[74:77], v[210:213], v[90:93]
	v_mfma_i32_16x16x64_i8 v[142:145], v[70:73], v[190:193], v[142:145]
	v_mfma_i32_16x16x64_i8 v[138:141], v[78:81], v[190:193], v[138:141]
	v_mfma_i32_16x16x64_i8 v[126:129], v[70:73], v[198:201], v[126:129]
	v_mfma_i32_16x16x64_i8 v[122:125], v[78:81], v[198:201], v[122:125]
	v_mfma_i32_16x16x64_i8 v[110:113], v[70:73], v[206:209], v[110:113]
	v_mfma_i32_16x16x64_i8 v[106:109], v[78:81], v[206:209], v[106:109]
	v_mfma_i32_16x16x64_i8 v[94:97], v[70:73], v[214:217], v[94:97]
	v_mfma_i32_16x16x64_i8 v[90:93], v[78:81], v[214:217], v[90:93]
	s_setprio 0
	s_setprio 1
	v_mfma_i32_16x16x64_i8 v[134:137], v[146:149], v[186:189], v[134:137]
	v_mfma_i32_16x16x64_i8 v[130:133], v[172:175], v[186:189], v[130:133]
	v_mfma_i32_16x16x64_i8 v[118:121], v[146:149], v[194:197], v[118:121]
	v_mfma_i32_16x16x64_i8 v[114:117], v[172:175], v[194:197], v[114:117]
	v_mfma_i32_16x16x64_i8 v[102:105], v[146:149], v[202:205], v[102:105]
	v_mfma_i32_16x16x64_i8 v[98:101], v[172:175], v[202:205], v[98:101]
	v_mfma_i32_16x16x64_i8 v[86:89], v[146:149], v[210:213], v[86:89]
	v_mfma_i32_16x16x64_i8 v[82:85], v[172:175], v[210:213], v[82:85]
	v_mfma_i32_16x16x64_i8 v[134:137], v[150:153], v[190:193], v[134:137]
	v_mfma_i32_16x16x64_i8 v[130:133], v[182:185], v[190:193], v[130:133]
	v_mfma_i32_16x16x64_i8 v[118:121], v[150:153], v[198:201], v[118:121]
	v_mfma_i32_16x16x64_i8 v[114:117], v[182:185], v[198:201], v[114:117]
	v_mfma_i32_16x16x64_i8 v[102:105], v[150:153], v[206:209], v[102:105]
	v_mfma_i32_16x16x64_i8 v[98:101], v[182:185], v[206:209], v[98:101]
	v_mfma_i32_16x16x64_i8 v[86:89], v[150:153], v[214:217], v[86:89]
	v_mfma_i32_16x16x64_i8 v[82:85], v[182:185], v[214:217], v[82:85]
	s_setprio 0
	s_barrier
	s_add_i32 s52, s43, s33
	s_mov_b32 m0, s52
	ds_read_b128 v[186:189], v180 offset:16384
	ds_read_b128 v[190:193], v180 offset:17408
	ds_read_b128 v[194:197], v180 offset:18432
	ds_read_b128 v[198:201], v180 offset:19456
	ds_read_b128 v[202:205], v180 offset:20480
	ds_read_b128 v[206:209], v180 offset:21504
	ds_read_b128 v[210:213], v180 offset:22528
	ds_read_b128 v[214:217], v180 offset:23552
	global_load_lds_dwordx4 v156, s[24:25]
	s_add_i32 m0, s52, 0x2000
	s_add_u32 s52, s24, 0x4000
	s_addc_u32 s53, s25, 0
	s_add_i32 s54, s44, s33
	global_load_lds_dwordx4 v160, s[24:25]
	s_mov_b32 m0, s54
	s_nop 0
	global_load_lds_dwordx4 v156, s[52:53]
	s_add_i32 m0, s54, 0x2000
	s_nop 0
	global_load_lds_dwordx4 v160, s[52:53]
	s_waitcnt vmcnt(6)
	s_waitcnt lgkmcnt(0)
	s_barrier
	s_setprio 1
	s_waitcnt lgkmcnt(0)
	v_mfma_i32_16x16x64_i8 v[62:65], v[66:69], v[186:189], v[62:65]
	v_mfma_i32_16x16x64_i8 v[58:61], v[74:77], v[186:189], v[58:61]
	v_mfma_i32_16x16x64_i8 v[46:49], v[66:69], v[194:197], v[46:49]
	v_mfma_i32_16x16x64_i8 v[42:45], v[74:77], v[194:197], v[42:45]
	v_mfma_i32_16x16x64_i8 v[30:33], v[66:69], v[202:205], v[30:33]
	v_mfma_i32_16x16x64_i8 v[26:29], v[74:77], v[202:205], v[26:29]
	v_mfma_i32_16x16x64_i8 v[14:17], v[66:69], v[210:213], v[14:17]
	v_mfma_i32_16x16x64_i8 v[10:13], v[74:77], v[210:213], v[10:13]
	v_mfma_i32_16x16x64_i8 v[62:65], v[70:73], v[190:193], v[62:65]
	v_mfma_i32_16x16x64_i8 v[58:61], v[78:81], v[190:193], v[58:61]
	v_mfma_i32_16x16x64_i8 v[46:49], v[70:73], v[198:201], v[46:49]
	v_mfma_i32_16x16x64_i8 v[42:45], v[78:81], v[198:201], v[42:45]
	v_mfma_i32_16x16x64_i8 v[30:33], v[70:73], v[206:209], v[30:33]
	v_mfma_i32_16x16x64_i8 v[26:29], v[78:81], v[206:209], v[26:29]
	v_mfma_i32_16x16x64_i8 v[14:17], v[70:73], v[214:217], v[14:17]
	v_mfma_i32_16x16x64_i8 v[10:13], v[78:81], v[214:217], v[10:13]
	s_setprio 0
	s_setprio 1
	v_mfma_i32_16x16x64_i8 v[54:57], v[146:149], v[186:189], v[54:57]
	v_mfma_i32_16x16x64_i8 v[50:53], v[172:175], v[186:189], v[50:53]
	v_mfma_i32_16x16x64_i8 v[38:41], v[146:149], v[194:197], v[38:41]
	v_mfma_i32_16x16x64_i8 v[34:37], v[172:175], v[194:197], v[34:37]
	v_mfma_i32_16x16x64_i8 v[22:25], v[146:149], v[202:205], v[22:25]
	v_mfma_i32_16x16x64_i8 v[18:21], v[172:175], v[202:205], v[18:21]
	v_mfma_i32_16x16x64_i8 v[6:9], v[146:149], v[210:213], v[6:9]
	v_mfma_i32_16x16x64_i8 v[2:5], v[172:175], v[210:213], v[2:5]
	v_mfma_i32_16x16x64_i8 v[54:57], v[150:153], v[190:193], v[54:57]
	v_mfma_i32_16x16x64_i8 v[50:53], v[182:185], v[190:193], v[50:53]
	v_mfma_i32_16x16x64_i8 v[38:41], v[150:153], v[198:201], v[38:41]
	v_mfma_i32_16x16x64_i8 v[34:37], v[182:185], v[198:201], v[34:37]
	v_mfma_i32_16x16x64_i8 v[22:25], v[150:153], v[206:209], v[22:25]
	v_mfma_i32_16x16x64_i8 v[18:21], v[182:185], v[206:209], v[18:21]
	v_mfma_i32_16x16x64_i8 v[6:9], v[150:153], v[214:217], v[6:9]
	v_mfma_i32_16x16x64_i8 v[2:5], v[182:185], v[214:217], v[2:5]
	s_setprio 0
	s_barrier
; #define PG8_STAGE(bufoff, gbase, voff) do { _Pragma("unroll") for (int _i = 0; _i < 2; ++_i) \
;         __builtin_amdgcn_global_load_lds((const unsigned*)((const char*)(gbase) + (voff)[_i]), (LAS unsigned*)(lds + (bufoff) + ldsw + _i * 8192), 16, 0, 0); } while (0)
; #define PG8_LDA(dst, b, h) do { _Pragma("unroll") for (int m = 0; m < 4; ++m) _Pragma("unroll") for (int k = 0; k < 2; ++k) dst[m][k] = *(const LAS bf16x8*)(lds + PG8_SA(b, h) + aoff + m * 2048 + k * 1024); } while (0)
; #define PG8_LDB(dst, b, h) do { _Pragma("unroll") for (int n = 0; n < 2; ++n) _Pragma("unroll") for (int k = 0; k < 2; ++k) dst[n][k] = *(const LAS bf16x8*)(lds + PG8_SB(b, h) + boff + n * 2048 + k * 1024); } while (0)
; #define PG8_WAIT_V(n) asm volatile("s_waitcnt vmcnt(" #n ")" ::: "memory")
; #define PG8_WAIT_L(n) asm volatile("s_waitcnt lgkmcnt(" #n ")" ::: "memory")
; #define PG8_BAR __builtin_amdgcn_s_barrier()
; #define PG8_SCHED __builtin_amdgcn_sched_barrier(0)
; template <class Epi, class Sched, bool I8 = false>
; __device__ __forceinline__ void gemm_phase(LAS unsigned char* lds, const Gemm g, const Sched& S, const Epi& E) {
;     ...
;             PG8_LDB(B0, 1, 0); PG8_LDB(B1, 1, 1); PG8_SCHED; PG8_LDA(At, 1, 0); PG8_STAGE(PG8_SA(0, 1), a2 + hstepA, voffA);
;             PG8_WAIT_V(8); PG8_WAIT_L(0); PG8_BAR; PG8_MMA(0, 0, At, B0); PG8_MMA(0, 1, At, B1); PG8_BAR; PG8_SCHED;
;             PG8_LDA(At, 1, 1); PG8_STAGE(PG8_SB(1, 0), b3, voffB); PG8_STAGE(PG8_SB(1, 1), b3 + hstepB, voffB); PG8_STAGE(PG8_SA(1, 0), a3, voffA);
;             PG8_WAIT_V(8); PG8_WAIT_L(0); PG8_BAR; PG8_MMA(1, 0, At, B0); PG8_MMA(1, 1, At, B1); PG8_BAR; PG8_SCHED;
;         }
	s_add_i32 s52, 0, 0x18000
	s_add_i32 s53, 0, 0x1c000
	v_add_u32_e32 v78, s52, v176
	v_add_u32_e32 v162, s53, v176
	ds_read_b128 v[66:69], v78
	ds_read_b128 v[70:73], v78 offset:1024
	ds_read_b128 v[74:77], v78 offset:2048
	ds_read_b128 v[78:81], v78 offset:3072
	ds_read_b128 v[146:149], v162
	ds_read_b128 v[150:153], v162 offset:1024
	ds_read_b128 v[172:175], v162 offset:2048
	ds_read_b128 v[182:185], v162 offset:3072
	s_mov_b32 m0, s34
	s_nop 0
	global_load_lds_dwordx4 v154, s[26:27]
	s_mov_b32 m0, s35
	s_nop 0
	global_load_lds_dwordx4 v158, s[26:27]
	s_add_u32 s26, s26, 0x4000
	s_addc_u32 s27, s27, 0
	s_mov_b32 m0, s36
	ds_read_b128 v[186:189], v180 offset:32768
	ds_read_b128 v[190:193], v180 offset:33792
	ds_read_b128 v[194:197], v180 offset:34816
	ds_read_b128 v[198:201], v180 offset:35840
	ds_read_b128 v[202:205], v180 offset:36864
	ds_read_b128 v[206:209], v180 offset:37888
	ds_read_b128 v[210:213], v180 offset:38912
	ds_read_b128 v[214:217], v180 offset:39936
	global_load_lds_dwordx4 v154, s[26:27]
	s_mov_b32 m0, s37
	s_nop 0
	global_load_lds_dwordx4 v158, s[26:27]
	s_waitcnt vmcnt(8)
	s_waitcnt lgkmcnt(0)
	s_barrier
	s_setprio 1
	s_waitcnt lgkmcnt(0)
	v_mfma_i32_16x16x64_i8 v[142:145], v[66:69], v[186:189], v[142:145]
	v_mfma_i32_16x16x64_i8 v[138:141], v[74:77], v[186:189], v[138:141]
	v_mfma_i32_16x16x64_i8 v[126:129], v[66:69], v[194:197], v[126:129]
	v_mfma_i32_16x16x64_i8 v[122:125], v[74:77], v[194:197], v[122:125]
	v_mfma_i32_16x16x64_i8 v[110:113], v[66:69], v[202:205], v[110:113]
	v_mfma_i32_16x16x64_i8 v[106:109], v[74:77], v[202:205], v[106:109]
	v_mfma_i32_16x16x64_i8 v[94:97], v[66:69], v[210:213], v[94:97]
	v_mfma_i32_16x16x64_i8 v[90:93], v[74:77], v[210:213], v[90:93]
	v_mfma_i32_16x16x64_i8 v[142:145], v[70:73], v[190:193], v[142:145]
	v_mfma_i32_16x16x64_i8 v[138:141], v[78:81], v[190:193], v[138:141]
	v_mfma_i32_16x16x64_i8 v[126:129], v[70:73], v[198:201], v[126:129]
	v_mfma_i32_16x16x64_i8 v[122:125], v[78:81], v[198:201], v[122:125]
	v_mfma_i32_16x16x64_i8 v[110:113], v[70:73], v[206:209], v[110:113]
	v_mfma_i32_16x16x64_i8 v[106:109], v[78:81], v[206:209], v[106:109]
	v_mfma_i32_16x16x64_i8 v[94:97], v[70:73], v[214:217], v[94:97]
	v_mfma_i32_16x16x64_i8 v[90:93], v[78:81], v[214:217], v[90:93]
	s_setprio 0
	s_setprio 1
	v_mfma_i32_16x16x64_i8 v[134:137], v[146:149], v[186:189], v[134:137]
	v_mfma_i32_16x16x64_i8 v[130:133], v[172:175], v[186:189], v[130:133]
	v_mfma_i32_16x16x64_i8 v[118:121], v[146:149], v[194:197], v[118:121]
	v_mfma_i32_16x16x64_i8 v[114:117], v[172:175], v[194:197], v[114:117]
	v_mfma_i32_16x16x64_i8 v[102:105], v[146:149], v[202:205], v[102:105]
	v_mfma_i32_16x16x64_i8 v[98:101], v[172:175], v[202:205], v[98:101]
	v_mfma_i32_16x16x64_i8 v[86:89], v[146:149], v[210:213], v[86:89]
	v_mfma_i32_16x16x64_i8 v[82:85], v[172:175], v[210:213], v[82:85]
	v_mfma_i32_16x16x64_i8 v[134:137], v[150:153], v[190:193], v[134:137]
	v_mfma_i32_16x16x64_i8 v[130:133], v[182:185], v[190:193], v[130:133]
	v_mfma_i32_16x16x64_i8 v[118:121], v[150:153], v[198:201], v[118:121]
	v_mfma_i32_16x16x64_i8 v[114:117], v[182:185], v[198:201], v[114:117]
	v_mfma_i32_16x16x64_i8 v[102:105], v[150:153], v[206:209], v[102:105]
	v_mfma_i32_16x16x64_i8 v[98:101], v[182:185], v[206:209], v[98:101]
	v_mfma_i32_16x16x64_i8 v[86:89], v[150:153], v[214:217], v[86:89]
	v_mfma_i32_16x16x64_i8 v[82:85], v[182:185], v[214:217], v[82:85]
	s_setprio 0
	s_barrier
	s_add_u32 s26, s24, 0x8000
	s_addc_u32 s27, s25, 0
	s_add_i32 s52, s52, s33
	s_mov_b32 m0, s52
	ds_read_b128 v[186:189], v180 offset:49152
	ds_read_b128 v[190:193], v180 offset:50176
	ds_read_b128 v[194:197], v180 offset:51200
	ds_read_b128 v[198:201], v180 offset:52224
	ds_read_b128 v[202:205], v180 offset:53248
	ds_read_b128 v[206:209], v180 offset:54272
	ds_read_b128 v[210:213], v180 offset:55296
	ds_read_b128 v[214:217], v180 offset:56320
	global_load_lds_dwordx4 v156, s[26:27]
	s_add_i32 m0, s52, 0x2000
	s_add_u32 s24, s24, 0xc000
	v_lshl_add_u64 v[218:219], s[26:27], 0, v[160:161]
	s_addc_u32 s25, s25, 0
	s_add_i32 s26, s53, s33
	global_load_lds_dwordx4 v[218:219], off
	s_mov_b32 m0, s26
	s_nop 0
	global_load_lds_dwordx4 v156, s[24:25]
	s_add_i32 m0, s26, 0x2000
	s_nop 0
	global_load_lds_dwordx4 v160, s[24:25]
	s_waitcnt vmcnt(6)
	s_waitcnt lgkmcnt(0)
	s_barrier
	s_setprio 1
	s_waitcnt lgkmcnt(0)
	v_mfma_i32_16x16x64_i8 v[62:65], v[66:69], v[186:189], v[62:65]
	v_mfma_i32_16x16x64_i8 v[58:61], v[74:77], v[186:189], v[58:61]
	v_mfma_i32_16x16x64_i8 v[46:49], v[66:69], v[194:197], v[46:49]
	v_mfma_i32_16x16x64_i8 v[42:45], v[74:77], v[194:197], v[42:45]
	v_mfma_i32_16x16x64_i8 v[30:33], v[66:69], v[202:205], v[30:33]
	v_mfma_i32_16x16x64_i8 v[26:29], v[74:77], v[202:205], v[26:29]
	v_mfma_i32_16x16x64_i8 v[14:17], v[66:69], v[210:213], v[14:17]
	v_mfma_i32_16x16x64_i8 v[10:13], v[74:77], v[210:213], v[10:13]
	v_mfma_i32_16x16x64_i8 v[62:65], v[70:73], v[190:193], v[62:65]
	v_mfma_i32_16x16x64_i8 v[58:61], v[78:81], v[190:193], v[58:61]
	v_mfma_i32_16x16x64_i8 v[46:49], v[70:73], v[198:201], v[46:49]
	v_mfma_i32_16x16x64_i8 v[42:45], v[78:81], v[198:201], v[42:45]
	v_mfma_i32_16x16x64_i8 v[30:33], v[70:73], v[206:209], v[30:33]
	v_mfma_i32_16x16x64_i8 v[26:29], v[78:81], v[206:209], v[26:29]
	v_mfma_i32_16x16x64_i8 v[14:17], v[70:73], v[214:217], v[14:17]
	v_mfma_i32_16x16x64_i8 v[10:13], v[78:81], v[214:217], v[10:13]
	s_setprio 0
	s_setprio 1
	v_mfma_i32_16x16x64_i8 v[54:57], v[146:149], v[186:189], v[54:57]
	v_mfma_i32_16x16x64_i8 v[50:53], v[172:175], v[186:189], v[50:53]
	v_mfma_i32_16x16x64_i8 v[38:41], v[146:149], v[194:197], v[38:41]
	v_mfma_i32_16x16x64_i8 v[34:37], v[172:175], v[194:197], v[34:37]
	v_mfma_i32_16x16x64_i8 v[22:25], v[146:149], v[202:205], v[22:25]
	v_mfma_i32_16x16x64_i8 v[18:21], v[172:175], v[202:205], v[18:21]
	v_mfma_i32_16x16x64_i8 v[6:9], v[146:149], v[210:213], v[6:9]
	v_mfma_i32_16x16x64_i8 v[2:5], v[172:175], v[210:213], v[2:5]
	v_mfma_i32_16x16x64_i8 v[54:57], v[150:153], v[190:193], v[54:57]
	v_mfma_i32_16x16x64_i8 v[50:53], v[182:185], v[190:193], v[50:53]
	v_mfma_i32_16x16x64_i8 v[38:41], v[150:153], v[198:201], v[38:41]
	v_mfma_i32_16x16x64_i8 v[34:37], v[182:185], v[198:201], v[34:37]
	v_mfma_i32_16x16x64_i8 v[22:25], v[150:153], v[206:209], v[22:25]
	v_mfma_i32_16x16x64_i8 v[18:21], v[182:185], v[206:209], v[18:21]
	v_mfma_i32_16x16x64_i8 v[6:9], v[150:153], v[214:217], v[6:9]
	v_mfma_i32_16x16x64_i8 v[2:5], v[182:185], v[214:217], v[2:5]
	s_setprio 0
	s_barrier
	s_add_i32 s51, s51, 2
	s_add_u32 s20, s20, 0x10000
	s_addc_u32 s21, s21, 0
	s_add_u32 s49, s49, 0x10000
	s_addc_u32 s50, s50, 0
	s_cmpk_gt_u32 s51, 0x53
	s_cbranch_scc0 .LBB0_4168
	s_and_b64 vcc, exec, s[14:15]
	s_cbranch_vccz .LBB0_4171
	s_barrier
